# v12 + trailing half issues its A-half-0 refill late in the preceding MFMA block (4/4 staging for both halves)
# baseline (speedup 1.0000x reference)
; #define PG8_STAGE(bufoff, gbase, voff) do { _Pragma("unroll") for (int _i = 0; _i < 2; ++_i) \
;         __builtin_amdgcn_global_load_lds((const unsigned*)((const char*)(gbase) + (voff)[_i]), (PG8_LAS unsigned*)(lds + (bufoff) + ldsw + _i * 8192), 16, 0, 0); } while (0)
; #define PG8_LDA(dst, b, h) do { _Pragma("unroll") for (int m = 0; m < 4; ++m) _Pragma("unroll") for (int k = 0; k < 2; ++k) dst[m][k] = *(const PG8_LAS bf16x8*)(lds + PG8_SA(b, h) + aoff + m * 2048 + k * 1024); } while (0)
; #define PG8_LDB(dst, b, h) do { _Pragma("unroll") for (int n = 0; n < 2; ++n) _Pragma("unroll") for (int k = 0; k < 2; ++k) dst[n][k] = *(const PG8_LAS bf16x8*)(lds + PG8_SB(b, h) + boff + n * 2048 + k * 1024); } while (0)
; #define PG8_MMA(ai, bj, At, Bt) do { __builtin_amdgcn_s_setprio(1); _Pragma("unroll") for (int m = 0; m < 4; ++m) _Pragma("unroll") for (int n = 0; n < 2; ++n) _Pragma("unroll") for (int k = 0; k < 2; ++k) \
;         acc[ai][bj][m][n] = __builtin_amdgcn_mfma_f32_16x16x32_bf16(Bt[n][k], At[m][k], acc[ai][bj][m][n], 0, 0, 0); __builtin_amdgcn_s_setprio(0); } while (0)
; #define PG8_WAIT_V(n) asm volatile("s_waitcnt vmcnt(" #n ")" ::: "memory")
; #define PG8_WAIT_L(n) asm volatile("s_waitcnt lgkmcnt(" #n ")" ::: "memory")
; #define PG8_BAR __builtin_amdgcn_s_barrier()
; #define PG8_SCHED __builtin_amdgcn_sched_barrier(0)
; template <class Epi, class Sched, bool ALIGN_EPI = false, bool SP2 = false>
; __device__ __forceinline__ void gemm_phase(PG8_LAS unsigned char* lds, const Gemm g, const Sched& S, const Epi& E) {
;     ...
;             PG8_LDB(B0, 0, 0); PG8_LDB(B1, 0, 1); PG8_SCHED; PG8_LDA(At, 0, 0); PG8_STAGE(PG8_SA(1, 1), a1 + hA, voffA);
;             PG8_WAIT_V(8); PG8_WAIT_L(0); PG8_BAR; PG8_MMA(0, 0, At, B0); PG8_MMA(0, 1, At, B1); PG8_BAR; PG8_SCHED;
;             PG8_LDA(At, 0, 1); PG8_STAGE(PG8_SB(0, 0), b2, voffB); PG8_STAGE(PG8_SB(0, 1), b2 + hB, voffB); PG8_STAGE(PG8_SA(0, 0), a2, voffA);
;             PG8_WAIT_V(8); PG8_WAIT_L(0); PG8_BAR; PG8_MMA(1, 0, At, B0); PG8_MMA(1, 1, At, B1); PG8_BAR; PG8_SCHED;
.Lkt_0:
	ds_read_b128 v[130:133], v229
	ds_read_b128 v[134:137], v229 offset:1024
	ds_read_b128 v[138:141], v229 offset:2048
	ds_read_b128 v[142:145], v229 offset:3072
	ds_read_b128 v[146:149], v230
	ds_read_b128 v[150:153], v230 offset:1024
	ds_read_b128 v[154:157], v230 offset:2048
	ds_read_b128 v[158:161], v230 offset:3072
	s_add_u32 s64, s62, 0xfff80080
	s_addc_u32 s65, s63, -1
	s_cmp_eq_u32 s97, 28
	s_cselect_b32 s67, s11, s65
	s_cselect_b32 s66, s33, s64
	s_cselect_b32 s65, s53, s96
	s_cselect_b32 s64, s55, s61
	s_add_i32 m0, s74, 0xc000
	ds_read_b128 v[162:165], v231
	ds_read_b128 v[166:169], v231 offset:1024
	ds_read_b128 v[170:173], v231 offset:2048
	ds_read_b128 v[174:177], v231 offset:3072
	ds_read_b128 v[178:181], v231 offset:4096
	ds_read_b128 v[182:185], v231 offset:5120
	ds_read_b128 v[186:189], v231 offset:6144
	ds_read_b128 v[190:193], v231 offset:7168
	global_load_lds_dwordx4 v212, s[62:63]
	s_add_i32 m0, s74, 0xe000
	s_nop 0
	global_load_lds_dwordx4 v214, s[62:63]
	s_waitcnt vmcnt(8)
	s_waitcnt lgkmcnt(0)
	s_barrier
	s_waitcnt lgkmcnt(0)
	v_mfma_f32_16x16x32_bf16 v[126:129], v[130:133], v[162:165], v[126:129]
	v_mfma_f32_16x16x32_bf16 v[122:125], v[138:141], v[162:165], v[122:125]
	v_mfma_f32_16x16x32_bf16 v[110:113], v[130:133], v[170:173], v[110:113]
	v_mfma_f32_16x16x32_bf16 v[106:109], v[138:141], v[170:173], v[106:109]
	v_mfma_f32_16x16x32_bf16 v[94:97], v[130:133], v[178:181], v[94:97]
	v_mfma_f32_16x16x32_bf16 v[90:93], v[138:141], v[178:181], v[90:93]
	v_mfma_f32_16x16x32_bf16 v[78:81], v[130:133], v[186:189], v[78:81]
	v_mfma_f32_16x16x32_bf16 v[74:77], v[138:141], v[186:189], v[74:77]
	v_mfma_f32_16x16x32_bf16 v[126:129], v[134:137], v[166:169], v[126:129]
	v_mfma_f32_16x16x32_bf16 v[122:125], v[142:145], v[166:169], v[122:125]
	v_mfma_f32_16x16x32_bf16 v[110:113], v[134:137], v[174:177], v[110:113]
	v_mfma_f32_16x16x32_bf16 v[106:109], v[142:145], v[174:177], v[106:109]
	v_mfma_f32_16x16x32_bf16 v[94:97], v[134:137], v[182:185], v[94:97]
	v_mfma_f32_16x16x32_bf16 v[90:93], v[142:145], v[182:185], v[90:93]
	v_mfma_f32_16x16x32_bf16 v[78:81], v[134:137], v[190:193], v[78:81]
	v_mfma_f32_16x16x32_bf16 v[74:77], v[142:145], v[190:193], v[74:77]
	v_mfma_f32_16x16x32_bf16 v[118:121], v[146:149], v[162:165], v[118:121]
	v_mfma_f32_16x16x32_bf16 v[114:117], v[154:157], v[162:165], v[114:117]
	v_mfma_f32_16x16x32_bf16 v[102:105], v[146:149], v[170:173], v[102:105]
	v_mfma_f32_16x16x32_bf16 v[98:101], v[154:157], v[170:173], v[98:101]
	s_mov_b32 m0, s74
	v_mfma_f32_16x16x32_bf16 v[86:89], v[146:149], v[178:181], v[86:89]
	global_load_lds_dwordx4 v194, s[66:67]
	v_mfma_f32_16x16x32_bf16 v[82:85], v[154:157], v[178:181], v[82:85]
	s_mov_b32 m0, s75
	v_mfma_f32_16x16x32_bf16 v[70:73], v[146:149], v[186:189], v[70:73]
	global_load_lds_dwordx4 v198, s[66:67]
	v_mfma_f32_16x16x32_bf16 v[66:69], v[154:157], v[186:189], v[66:69]
	v_mfma_f32_16x16x32_bf16 v[118:121], v[150:153], v[166:169], v[118:121]
	v_mfma_f32_16x16x32_bf16 v[114:117], v[158:161], v[166:169], v[114:117]
	v_mfma_f32_16x16x32_bf16 v[102:105], v[150:153], v[174:177], v[102:105]
	v_mfma_f32_16x16x32_bf16 v[98:101], v[158:161], v[174:177], v[98:101]
	v_mfma_f32_16x16x32_bf16 v[86:89], v[150:153], v[182:185], v[86:89]
	v_mfma_f32_16x16x32_bf16 v[82:85], v[158:161], v[182:185], v[82:85]
	v_mfma_f32_16x16x32_bf16 v[70:73], v[150:153], v[190:193], v[70:73]
	v_mfma_f32_16x16x32_bf16 v[66:69], v[158:161], v[190:193], v[66:69]
	s_barrier
	s_add_i32 vcc_lo, s84, s73
	s_add_u32 s34, s64, s38
	s_addc_u32 s35, s65, s39
	s_mov_b32 m0, vcc_lo
	ds_read_b128 v[162:165], v231 offset:16384
	ds_read_b128 v[166:169], v231 offset:17408
	ds_read_b128 v[170:173], v231 offset:18432
	ds_read_b128 v[174:177], v231 offset:19456
	ds_read_b128 v[178:181], v231 offset:20480
	ds_read_b128 v[182:185], v231 offset:21504
	ds_read_b128 v[186:189], v231 offset:22528
	ds_read_b128 v[190:193], v231 offset:23552
	global_load_lds_dwordx4 v196, s[64:65]
	s_add_i32 m0, vcc_lo, 0x2000
	s_add_u32 vcc_lo, s64, 0x80000
	s_addc_u32 vcc_hi, s65, 0
	s_add_i32 s86, s85, s73
	global_load_lds_dwordx4 v200, s[64:65]
	s_mov_b32 m0, s86
	s_nop 0
	global_load_lds_dwordx4 v196, vcc
	s_add_i32 m0, s86, 0x2000
	s_nop 0
	global_load_lds_dwordx4 v200, vcc
	s_add_u32 s98, s66, s38
	s_addc_u32 s99, s67, s39
	s_waitcnt vmcnt(8)
	s_waitcnt lgkmcnt(0)
	s_barrier
	s_waitcnt lgkmcnt(0)
	v_mfma_f32_16x16x32_bf16 v[62:65], v[130:133], v[162:165], v[62:65]
	v_mfma_f32_16x16x32_bf16 v[58:61], v[138:141], v[162:165], v[58:61]
	v_mfma_f32_16x16x32_bf16 v[46:49], v[130:133], v[170:173], v[46:49]
	v_mfma_f32_16x16x32_bf16 v[42:45], v[138:141], v[170:173], v[42:45]
	v_mfma_f32_16x16x32_bf16 v[30:33], v[130:133], v[178:181], v[30:33]
	v_mfma_f32_16x16x32_bf16 v[26:29], v[138:141], v[178:181], v[26:29]
	v_mfma_f32_16x16x32_bf16 v[14:17], v[130:133], v[186:189], v[14:17]
	v_mfma_f32_16x16x32_bf16 v[10:13], v[138:141], v[186:189], v[10:13]
	v_mfma_f32_16x16x32_bf16 v[62:65], v[134:137], v[166:169], v[62:65]
	v_mfma_f32_16x16x32_bf16 v[58:61], v[142:145], v[166:169], v[58:61]
	v_mfma_f32_16x16x32_bf16 v[46:49], v[134:137], v[174:177], v[46:49]
	v_mfma_f32_16x16x32_bf16 v[42:45], v[142:145], v[174:177], v[42:45]
	v_mfma_f32_16x16x32_bf16 v[30:33], v[134:137], v[182:185], v[30:33]
	v_mfma_f32_16x16x32_bf16 v[26:29], v[142:145], v[182:185], v[26:29]
	v_mfma_f32_16x16x32_bf16 v[14:17], v[134:137], v[190:193], v[14:17]
	v_mfma_f32_16x16x32_bf16 v[10:13], v[142:145], v[190:193], v[10:13]
	v_mfma_f32_16x16x32_bf16 v[54:57], v[146:149], v[162:165], v[54:57]
	v_mfma_f32_16x16x32_bf16 v[50:53], v[154:157], v[162:165], v[50:53]
	v_mfma_f32_16x16x32_bf16 v[38:41], v[146:149], v[170:173], v[38:41]
	v_mfma_f32_16x16x32_bf16 v[34:37], v[154:157], v[170:173], v[34:37]
	v_mfma_f32_16x16x32_bf16 v[22:25], v[146:149], v[178:181], v[22:25]
	v_mfma_f32_16x16x32_bf16 v[18:21], v[154:157], v[178:181], v[18:21]
	v_mfma_f32_16x16x32_bf16 v[6:9], v[146:149], v[186:189], v[6:9]
	v_mfma_f32_16x16x32_bf16 v[2:5], v[154:157], v[186:189], v[2:5]
	v_mfma_f32_16x16x32_bf16 v[54:57], v[150:153], v[166:169], v[54:57]
	v_mfma_f32_16x16x32_bf16 v[50:53], v[158:161], v[166:169], v[50:53]
	v_mfma_f32_16x16x32_bf16 v[38:41], v[150:153], v[174:177], v[38:41]
	v_mfma_f32_16x16x32_bf16 v[34:37], v[158:161], v[174:177], v[34:37]
	v_mfma_f32_16x16x32_bf16 v[22:25], v[150:153], v[182:185], v[22:25]
	v_mfma_f32_16x16x32_bf16 v[18:21], v[158:161], v[182:185], v[18:21]
	v_mfma_f32_16x16x32_bf16 v[6:9], v[150:153], v[190:193], v[6:9]
	v_mfma_f32_16x16x32_bf16 v[2:5], v[158:161], v[190:193], v[2:5]
	s_barrier
; #define PG8_STAGE(bufoff, gbase, voff) do { _Pragma("unroll") for (int _i = 0; _i < 2; ++_i) \
;         __builtin_amdgcn_global_load_lds((const unsigned*)((const char*)(gbase) + (voff)[_i]), (PG8_LAS unsigned*)(lds + (bufoff) + ldsw + _i * 8192), 16, 0, 0); } while (0)
; #define PG8_LDA(dst, b, h) do { _Pragma("unroll") for (int m = 0; m < 4; ++m) _Pragma("unroll") for (int k = 0; k < 2; ++k) dst[m][k] = *(const PG8_LAS bf16x8*)(lds + PG8_SA(b, h) + aoff + m * 2048 + k * 1024); } while (0)
; #define PG8_LDB(dst, b, h) do { _Pragma("unroll") for (int n = 0; n < 2; ++n) _Pragma("unroll") for (int k = 0; k < 2; ++k) dst[n][k] = *(const PG8_LAS bf16x8*)(lds + PG8_SB(b, h) + boff + n * 2048 + k * 1024); } while (0)
; #define PG8_MMA(ai, bj, At, Bt) do { __builtin_amdgcn_s_setprio(1); _Pragma("unroll") for (int m = 0; m < 4; ++m) _Pragma("unroll") for (int n = 0; n < 2; ++n) _Pragma("unroll") for (int k = 0; k < 2; ++k) \
;         acc[ai][bj][m][n] = __builtin_amdgcn_mfma_f32_16x16x32_bf16(Bt[n][k], At[m][k], acc[ai][bj][m][n], 0, 0, 0); __builtin_amdgcn_s_setprio(0); } while (0)
; #define PG8_WAIT_V(n) asm volatile("s_waitcnt vmcnt(" #n ")" ::: "memory")
; #define PG8_WAIT_L(n) asm volatile("s_waitcnt lgkmcnt(" #n ")" ::: "memory")
; #define PG8_BAR __builtin_amdgcn_s_barrier()
; #define PG8_SCHED __builtin_amdgcn_sched_barrier(0)
; template <class Epi, class Sched, bool ALIGN_EPI = false, bool SP2 = false>
; __device__ __forceinline__ void gemm_phase(PG8_LAS unsigned char* lds, const Gemm g, const Sched& S, const Epi& E) {
;     ...
;             PG8_LDB(B0, 1, 0); PG8_LDB(B1, 1, 1); PG8_SCHED; PG8_LDA(At, 1, 0); PG8_STAGE(PG8_SA(0, 1), a2 + hA, voffA);
;             PG8_WAIT_V(8); PG8_WAIT_L(0); PG8_BAR; PG8_MMA(0, 0, At, B0); PG8_MMA(0, 1, At, B1); PG8_BAR; PG8_SCHED;
;             PG8_LDA(At, 1, 1); PG8_STAGE(PG8_SB(1, 0), b3, voffB); PG8_STAGE(PG8_SB(1, 1), b3 + hB, voffB); PG8_STAGE(PG8_SA(1, 0), a3, voffA);
;             PG8_WAIT_V(8); PG8_WAIT_L(0); PG8_BAR; PG8_MMA(1, 0, At, B0); PG8_MMA(1, 1, At, B1); PG8_BAR; PG8_SCHED;
	s_add_i32 s86, 0, 0x18000
	s_add_i32 vcc_lo, 0, 0x1c000
	v_add_u32_e32 v142, s86, v223
	v_add_u32_e32 v158, vcc_lo, v223
	ds_read_b128 v[130:133], v142
	ds_read_b128 v[134:137], v142 offset:1024
	ds_read_b128 v[138:141], v142 offset:2048
	ds_read_b128 v[142:145], v142 offset:3072
	ds_read_b128 v[146:149], v158
	ds_read_b128 v[150:153], v158 offset:1024
	ds_read_b128 v[154:157], v158 offset:2048
	ds_read_b128 v[158:161], v158 offset:3072
	s_add_u32 s66, s66, 0x80000
	s_addc_u32 s67, s67, 0
	s_mov_b32 m0, s76
	ds_read_b128 v[162:165], v231 offset:32768
	ds_read_b128 v[166:169], v231 offset:33792
	ds_read_b128 v[170:173], v231 offset:34816
	ds_read_b128 v[174:177], v231 offset:35840
	ds_read_b128 v[178:181], v231 offset:36864
	ds_read_b128 v[182:185], v231 offset:37888
	ds_read_b128 v[186:189], v231 offset:38912
	ds_read_b128 v[190:193], v231 offset:39936
	global_load_lds_dwordx4 v194, s[66:67]
	s_mov_b32 m0, s77
	s_nop 0
	global_load_lds_dwordx4 v198, s[66:67]
	s_waitcnt vmcnt(8)
	s_waitcnt lgkmcnt(0)
	s_barrier
	s_waitcnt lgkmcnt(0)
	v_mfma_f32_16x16x32_bf16 v[126:129], v[130:133], v[162:165], v[126:129]
	v_mfma_f32_16x16x32_bf16 v[122:125], v[138:141], v[162:165], v[122:125]
	v_mfma_f32_16x16x32_bf16 v[110:113], v[130:133], v[170:173], v[110:113]
	v_mfma_f32_16x16x32_bf16 v[106:109], v[138:141], v[170:173], v[106:109]
	v_mfma_f32_16x16x32_bf16 v[94:97], v[130:133], v[178:181], v[94:97]
	v_mfma_f32_16x16x32_bf16 v[90:93], v[138:141], v[178:181], v[90:93]
	v_mfma_f32_16x16x32_bf16 v[78:81], v[130:133], v[186:189], v[78:81]
	v_mfma_f32_16x16x32_bf16 v[74:77], v[138:141], v[186:189], v[74:77]
	v_mfma_f32_16x16x32_bf16 v[126:129], v[134:137], v[166:169], v[126:129]
	v_mfma_f32_16x16x32_bf16 v[122:125], v[142:145], v[166:169], v[122:125]
	v_mfma_f32_16x16x32_bf16 v[110:113], v[134:137], v[174:177], v[110:113]
	v_mfma_f32_16x16x32_bf16 v[106:109], v[142:145], v[174:177], v[106:109]
	v_mfma_f32_16x16x32_bf16 v[94:97], v[134:137], v[182:185], v[94:97]
	v_mfma_f32_16x16x32_bf16 v[90:93], v[142:145], v[182:185], v[90:93]
	v_mfma_f32_16x16x32_bf16 v[78:81], v[134:137], v[190:193], v[78:81]
	v_mfma_f32_16x16x32_bf16 v[74:77], v[142:145], v[190:193], v[74:77]
	v_mfma_f32_16x16x32_bf16 v[118:121], v[146:149], v[162:165], v[118:121]
	v_mfma_f32_16x16x32_bf16 v[114:117], v[154:157], v[162:165], v[114:117]
	v_mfma_f32_16x16x32_bf16 v[102:105], v[146:149], v[170:173], v[102:105]
	v_mfma_f32_16x16x32_bf16 v[98:101], v[154:157], v[170:173], v[98:101]
	s_mov_b32 m0, s81
	v_mfma_f32_16x16x32_bf16 v[86:89], v[146:149], v[178:181], v[86:89]
	global_load_lds_dwordx4 v194, s[98:99]
	v_mfma_f32_16x16x32_bf16 v[82:85], v[154:157], v[178:181], v[82:85]
	s_mov_b32 m0, s82
	v_mfma_f32_16x16x32_bf16 v[70:73], v[146:149], v[186:189], v[70:73]
	global_load_lds_dwordx4 v198, s[98:99]
	v_mfma_f32_16x16x32_bf16 v[66:69], v[154:157], v[186:189], v[66:69]
	v_mfma_f32_16x16x32_bf16 v[118:121], v[150:153], v[166:169], v[118:121]
	v_mfma_f32_16x16x32_bf16 v[114:117], v[158:161], v[166:169], v[114:117]
	v_mfma_f32_16x16x32_bf16 v[102:105], v[150:153], v[174:177], v[102:105]
	v_mfma_f32_16x16x32_bf16 v[98:101], v[158:161], v[174:177], v[98:101]
	v_mfma_f32_16x16x32_bf16 v[86:89], v[150:153], v[182:185], v[86:89]
	v_mfma_f32_16x16x32_bf16 v[82:85], v[158:161], v[182:185], v[82:85]
	v_mfma_f32_16x16x32_bf16 v[70:73], v[150:153], v[190:193], v[70:73]
	v_mfma_f32_16x16x32_bf16 v[66:69], v[158:161], v[190:193], v[66:69]
	s_barrier
	s_add_i32 s66, s86, s73
	s_mov_b32 m0, s66
	ds_read_b128 v[162:165], v231 offset:49152
	ds_read_b128 v[166:169], v231 offset:50176
	ds_read_b128 v[170:173], v231 offset:51200
	ds_read_b128 v[174:177], v231 offset:52224
	ds_read_b128 v[178:181], v231 offset:53248
	ds_read_b128 v[182:185], v231 offset:54272
	ds_read_b128 v[186:189], v231 offset:55296
	ds_read_b128 v[190:193], v231 offset:56320
	global_load_lds_dwordx4 v196, s[34:35]
	s_add_i32 m0, s66, 0x2000
	s_add_u32 s64, s64, 0x80080
	s_addc_u32 s65, s65, 0
	s_add_i32 s66, vcc_lo, s73
	global_load_lds_dwordx4 v200, s[34:35]
	s_mov_b32 m0, s66
	s_nop 0
	global_load_lds_dwordx4 v196, s[64:65]
	s_add_i32 m0, s66, 0x2000
	s_nop 0
	global_load_lds_dwordx4 v200, s[64:65]
	s_waitcnt vmcnt(8)
	s_waitcnt lgkmcnt(0)
	s_barrier
	s_waitcnt lgkmcnt(0)
	v_mfma_f32_16x16x32_bf16 v[62:65], v[130:133], v[162:165], v[62:65]
	v_mfma_f32_16x16x32_bf16 v[58:61], v[138:141], v[162:165], v[58:61]
	v_mfma_f32_16x16x32_bf16 v[46:49], v[130:133], v[170:173], v[46:49]
	v_mfma_f32_16x16x32_bf16 v[42:45], v[138:141], v[170:173], v[42:45]
	v_mfma_f32_16x16x32_bf16 v[30:33], v[130:133], v[178:181], v[30:33]
	v_mfma_f32_16x16x32_bf16 v[26:29], v[138:141], v[178:181], v[26:29]
	v_mfma_f32_16x16x32_bf16 v[14:17], v[130:133], v[186:189], v[14:17]
	v_mfma_f32_16x16x32_bf16 v[10:13], v[138:141], v[186:189], v[10:13]
	v_mfma_f32_16x16x32_bf16 v[62:65], v[134:137], v[166:169], v[62:65]
	v_mfma_f32_16x16x32_bf16 v[58:61], v[142:145], v[166:169], v[58:61]
	v_mfma_f32_16x16x32_bf16 v[46:49], v[134:137], v[174:177], v[46:49]
	v_mfma_f32_16x16x32_bf16 v[42:45], v[142:145], v[174:177], v[42:45]
	v_mfma_f32_16x16x32_bf16 v[30:33], v[134:137], v[182:185], v[30:33]
	v_mfma_f32_16x16x32_bf16 v[26:29], v[142:145], v[182:185], v[26:29]
	v_mfma_f32_16x16x32_bf16 v[14:17], v[134:137], v[190:193], v[14:17]
	v_mfma_f32_16x16x32_bf16 v[10:13], v[142:145], v[190:193], v[10:13]
	v_mfma_f32_16x16x32_bf16 v[54:57], v[146:149], v[162:165], v[54:57]
	v_mfma_f32_16x16x32_bf16 v[50:53], v[154:157], v[162:165], v[50:53]
	v_mfma_f32_16x16x32_bf16 v[38:41], v[146:149], v[170:173], v[38:41]
	v_mfma_f32_16x16x32_bf16 v[34:37], v[154:157], v[170:173], v[34:37]
	v_mfma_f32_16x16x32_bf16 v[22:25], v[146:149], v[178:181], v[22:25]
	v_mfma_f32_16x16x32_bf16 v[18:21], v[154:157], v[178:181], v[18:21]
	v_mfma_f32_16x16x32_bf16 v[6:9], v[146:149], v[186:189], v[6:9]
	v_mfma_f32_16x16x32_bf16 v[2:5], v[154:157], v[186:189], v[2:5]
	v_mfma_f32_16x16x32_bf16 v[54:57], v[150:153], v[166:169], v[54:57]
	v_mfma_f32_16x16x32_bf16 v[50:53], v[158:161], v[166:169], v[50:53]
	v_mfma_f32_16x16x32_bf16 v[38:41], v[150:153], v[174:177], v[38:41]
	v_mfma_f32_16x16x32_bf16 v[34:37], v[158:161], v[174:177], v[34:37]
	v_mfma_f32_16x16x32_bf16 v[22:25], v[150:153], v[182:185], v[22:25]
	v_mfma_f32_16x16x32_bf16 v[18:21], v[158:161], v[182:185], v[18:21]
	v_mfma_f32_16x16x32_bf16 v[6:9], v[150:153], v[190:193], v[6:9]
	v_mfma_f32_16x16x32_bf16 v[2:5], v[158:161], v[190:193], v[2:5]
	s_barrier
	s_add_i32 s97, s97, 2
	s_add_u32 s62, s62, 0x100
	s_addc_u32 s63, s63, 0
	s_add_u32 s61, s61, 0x100
	s_addc_u32 s96, s96, 0
	s_cmp_gt_u32 s97, 29
	s_cbranch_scc0 .Lkt_0

; #define PG8_STAGE(bufoff, gbase, voff) do { _Pragma("unroll") for (int _i = 0; _i < 2; ++_i) \
;         __builtin_amdgcn_global_load_lds((const unsigned*)((const char*)(gbase) + (voff)[_i]), (PG8_LAS unsigned*)(lds + (bufoff) + ldsw + _i * 8192), 16, 0, 0); } while (0)
; #define PG8_LDA(dst, b, h) do { _Pragma("unroll") for (int m = 0; m < 4; ++m) _Pragma("unroll") for (int k = 0; k < 2; ++k) dst[m][k] = *(const PG8_LAS bf16x8*)(lds + PG8_SA(b, h) + aoff + m * 2048 + k * 1024); } while (0)
; #define PG8_LDB(dst, b, h) do { _Pragma("unroll") for (int n = 0; n < 2; ++n) _Pragma("unroll") for (int k = 0; k < 2; ++k) dst[n][k] = *(const PG8_LAS bf16x8*)(lds + PG8_SB(b, h) + boff + n * 2048 + k * 1024); } while (0)
; #define PG8_MMA(ai, bj, At, Bt) do { __builtin_amdgcn_s_setprio(1); _Pragma("unroll") for (int m = 0; m < 4; ++m) _Pragma("unroll") for (int n = 0; n < 2; ++n) _Pragma("unroll") for (int k = 0; k < 2; ++k) \
;         acc[ai][bj][m][n] = __builtin_amdgcn_mfma_f32_16x16x32_bf16(Bt[n][k], At[m][k], acc[ai][bj][m][n], 0, 0, 0); __builtin_amdgcn_s_setprio(0); } while (0)
; #define PG8_WAIT_V(n) asm volatile("s_waitcnt vmcnt(" #n ")" ::: "memory")
; #define PG8_WAIT_L(n) asm volatile("s_waitcnt lgkmcnt(" #n ")" ::: "memory")
; #define PG8_BAR __builtin_amdgcn_s_barrier()
; #define PG8_SCHED __builtin_amdgcn_sched_barrier(0)
; template <class Epi, class Sched, bool ALIGN_EPI = false, bool SP2 = false>
; __device__ __forceinline__ void gemm_phase(PG8_LAS unsigned char* lds, const Gemm g, const Sched& S, const Epi& E) {
;     ...
;             PG8_LDB(B0, 0, 0); PG8_LDB(B1, 0, 1); PG8_SCHED; PG8_LDA(At, 0, 0); PG8_STAGE(PG8_SA(1, 1), a1 + hA, voffA);
;             PG8_WAIT_V(8); PG8_WAIT_L(0); PG8_BAR; PG8_MMA(0, 0, At, B0); PG8_MMA(0, 1, At, B1); PG8_BAR; PG8_SCHED;
;             PG8_LDA(At, 0, 1); PG8_STAGE(PG8_SB(0, 0), b2, voffB); PG8_STAGE(PG8_SB(0, 1), b2 + hB, voffB); PG8_STAGE(PG8_SA(0, 0), a2, voffA);
;             PG8_WAIT_V(8); PG8_WAIT_L(0); PG8_BAR; PG8_MMA(1, 0, At, B0); PG8_MMA(1, 1, At, B1); PG8_BAR; PG8_SCHED;
.Lkt_1:
	ds_read_b128 v[146:149], v156
	ds_read_b128 v[150:153], v156 offset:1024
	ds_read_b128 v[160:163], v156 offset:2048
	ds_read_b128 v[164:167], v156 offset:3072
	ds_read_b128 v[168:171], v157
	ds_read_b128 v[172:175], v157 offset:1024
	ds_read_b128 v[176:179], v157 offset:2048
	ds_read_b128 v[180:183], v157 offset:3072
	s_add_u32 s18, s42, 0xfffc0080
	s_addc_u32 s19, s43, -1
	s_cmp_eq_u32 s72, 12
	s_cselect_b32 s47, s23, s19
	s_cselect_b32 s46, s67, s18
	s_cselect_b32 s45, s21, s71
	s_cselect_b32 s44, s69, s70
	s_add_i32 m0, s41, 0xc000
	ds_read_b128 v[184:187], v158
	ds_read_b128 v[188:191], v158 offset:1024
	ds_read_b128 v[192:195], v158 offset:2048
	ds_read_b128 v[196:199], v158 offset:3072
	ds_read_b128 v[200:203], v158 offset:4096
	ds_read_b128 v[204:207], v158 offset:5120
	ds_read_b128 v[208:211], v158 offset:6144
	ds_read_b128 v[212:215], v158 offset:7168
	global_load_lds_dwordx4 v138, s[42:43]
	s_add_i32 m0, s41, 0xe000
	s_nop 0
	global_load_lds_dwordx4 v140, s[42:43]
	s_waitcnt vmcnt(8)
	s_waitcnt lgkmcnt(0)
	s_barrier
	s_waitcnt lgkmcnt(0)
	v_mfma_f32_16x16x32_bf16 v[126:129], v[146:149], v[184:187], v[126:129]
	v_mfma_f32_16x16x32_bf16 v[122:125], v[160:163], v[184:187], v[122:125]
	v_mfma_f32_16x16x32_bf16 v[114:117], v[146:149], v[192:195], v[114:117]
	v_mfma_f32_16x16x32_bf16 v[106:109], v[160:163], v[192:195], v[106:109]
	v_mfma_f32_16x16x32_bf16 v[98:101], v[146:149], v[200:203], v[98:101]
	v_mfma_f32_16x16x32_bf16 v[90:93], v[160:163], v[200:203], v[90:93]
	v_mfma_f32_16x16x32_bf16 v[82:85], v[146:149], v[208:211], v[82:85]
	v_mfma_f32_16x16x32_bf16 v[74:77], v[160:163], v[208:211], v[74:77]
	v_mfma_f32_16x16x32_bf16 v[126:129], v[150:153], v[188:191], v[126:129]
	v_mfma_f32_16x16x32_bf16 v[122:125], v[164:167], v[188:191], v[122:125]
	v_mfma_f32_16x16x32_bf16 v[114:117], v[150:153], v[196:199], v[114:117]
	v_mfma_f32_16x16x32_bf16 v[106:109], v[164:167], v[196:199], v[106:109]
	v_mfma_f32_16x16x32_bf16 v[98:101], v[150:153], v[204:207], v[98:101]
	v_mfma_f32_16x16x32_bf16 v[90:93], v[164:167], v[204:207], v[90:93]
	v_mfma_f32_16x16x32_bf16 v[82:85], v[150:153], v[212:215], v[82:85]
	v_mfma_f32_16x16x32_bf16 v[74:77], v[164:167], v[212:215], v[74:77]
	v_mfma_f32_16x16x32_bf16 v[118:121], v[168:171], v[184:187], v[118:121]
	v_mfma_f32_16x16x32_bf16 v[110:113], v[176:179], v[184:187], v[110:113]
	v_mfma_f32_16x16x32_bf16 v[102:105], v[168:171], v[192:195], v[102:105]
	v_mfma_f32_16x16x32_bf16 v[94:97], v[176:179], v[192:195], v[94:97]
	s_mov_b32 m0, s41
	v_mfma_f32_16x16x32_bf16 v[86:89], v[168:171], v[200:203], v[86:89]
	global_load_lds_dwordx4 v136, s[46:47]
	v_mfma_f32_16x16x32_bf16 v[78:81], v[176:179], v[200:203], v[78:81]
	s_mov_b32 m0, s53
	v_mfma_f32_16x16x32_bf16 v[70:73], v[168:171], v[208:211], v[70:73]
	global_load_lds_dwordx4 v132, s[46:47]
	v_mfma_f32_16x16x32_bf16 v[66:69], v[176:179], v[208:211], v[66:69]
	v_mfma_f32_16x16x32_bf16 v[118:121], v[172:175], v[188:191], v[118:121]
	v_mfma_f32_16x16x32_bf16 v[110:113], v[180:183], v[188:191], v[110:113]
	v_mfma_f32_16x16x32_bf16 v[102:105], v[172:175], v[196:199], v[102:105]
	v_mfma_f32_16x16x32_bf16 v[94:97], v[180:183], v[196:199], v[94:97]
	v_mfma_f32_16x16x32_bf16 v[86:89], v[172:175], v[204:207], v[86:89]
	v_mfma_f32_16x16x32_bf16 v[78:81], v[180:183], v[204:207], v[78:81]
	v_mfma_f32_16x16x32_bf16 v[70:73], v[172:175], v[212:215], v[70:73]
	v_mfma_f32_16x16x32_bf16 v[66:69], v[180:183], v[212:215], v[66:69]
	s_barrier
	s_add_i32 s18, s64, s52
	s_add_u32 s78, s44, s8
	s_addc_u32 s79, s45, s9
	s_mov_b32 m0, s18
	ds_read_b128 v[184:187], v158 offset:16384
	ds_read_b128 v[188:191], v158 offset:17408
	ds_read_b128 v[192:195], v158 offset:18432
	ds_read_b128 v[196:199], v158 offset:19456
	ds_read_b128 v[200:203], v158 offset:20480
	ds_read_b128 v[204:207], v158 offset:21504
	ds_read_b128 v[208:211], v158 offset:22528
	ds_read_b128 v[212:215], v158 offset:23552
	global_load_lds_dwordx4 v134, s[44:45]
	s_add_i32 m0, s18, 0x2000
	s_add_u32 s74, s44, 0x40000
	s_addc_u32 s75, s45, 0
	s_add_i32 s18, s65, s52
	global_load_lds_dwordx4 v130, s[44:45]
	s_mov_b32 m0, s18
	s_nop 0
	global_load_lds_dwordx4 v134, s[74:75]
	s_add_i32 m0, s18, 0x2000
	s_nop 0
	global_load_lds_dwordx4 v130, s[74:75]
	s_add_u32 s80, s46, s8
	s_addc_u32 s81, s47, s9
	s_waitcnt vmcnt(8)
	s_waitcnt lgkmcnt(0)
	s_barrier
	s_waitcnt lgkmcnt(0)
	v_mfma_f32_16x16x32_bf16 v[62:65], v[146:149], v[184:187], v[62:65]
	v_mfma_f32_16x16x32_bf16 v[58:61], v[160:163], v[184:187], v[58:61]
	v_mfma_f32_16x16x32_bf16 v[50:53], v[146:149], v[192:195], v[50:53]
	v_mfma_f32_16x16x32_bf16 v[42:45], v[160:163], v[192:195], v[42:45]
	v_mfma_f32_16x16x32_bf16 v[34:37], v[146:149], v[200:203], v[34:37]
	v_mfma_f32_16x16x32_bf16 v[26:29], v[160:163], v[200:203], v[26:29]
	v_mfma_f32_16x16x32_bf16 v[18:21], v[146:149], v[208:211], v[18:21]
	v_mfma_f32_16x16x32_bf16 v[10:13], v[160:163], v[208:211], v[10:13]
	v_mfma_f32_16x16x32_bf16 v[62:65], v[150:153], v[188:191], v[62:65]
	v_mfma_f32_16x16x32_bf16 v[58:61], v[164:167], v[188:191], v[58:61]
	v_mfma_f32_16x16x32_bf16 v[50:53], v[150:153], v[196:199], v[50:53]
	v_mfma_f32_16x16x32_bf16 v[42:45], v[164:167], v[196:199], v[42:45]
	v_mfma_f32_16x16x32_bf16 v[34:37], v[150:153], v[204:207], v[34:37]
	v_mfma_f32_16x16x32_bf16 v[26:29], v[164:167], v[204:207], v[26:29]
	v_mfma_f32_16x16x32_bf16 v[18:21], v[150:153], v[212:215], v[18:21]
	v_mfma_f32_16x16x32_bf16 v[10:13], v[164:167], v[212:215], v[10:13]
	v_mfma_f32_16x16x32_bf16 v[54:57], v[168:171], v[184:187], v[54:57]
	v_mfma_f32_16x16x32_bf16 v[46:49], v[176:179], v[184:187], v[46:49]
	v_mfma_f32_16x16x32_bf16 v[38:41], v[168:171], v[192:195], v[38:41]
	v_mfma_f32_16x16x32_bf16 v[30:33], v[176:179], v[192:195], v[30:33]
	v_mfma_f32_16x16x32_bf16 v[22:25], v[168:171], v[200:203], v[22:25]
	v_mfma_f32_16x16x32_bf16 v[14:17], v[176:179], v[200:203], v[14:17]
	v_mfma_f32_16x16x32_bf16 v[6:9], v[168:171], v[208:211], v[6:9]
	v_mfma_f32_16x16x32_bf16 v[2:5], v[176:179], v[208:211], v[2:5]
	v_mfma_f32_16x16x32_bf16 v[54:57], v[172:175], v[188:191], v[54:57]
	v_mfma_f32_16x16x32_bf16 v[46:49], v[180:183], v[188:191], v[46:49]
	v_mfma_f32_16x16x32_bf16 v[38:41], v[172:175], v[196:199], v[38:41]
	v_mfma_f32_16x16x32_bf16 v[30:33], v[180:183], v[196:199], v[30:33]
	v_mfma_f32_16x16x32_bf16 v[22:25], v[172:175], v[204:207], v[22:25]
	v_mfma_f32_16x16x32_bf16 v[14:17], v[180:183], v[204:207], v[14:17]
	v_mfma_f32_16x16x32_bf16 v[6:9], v[172:175], v[212:215], v[6:9]
	v_mfma_f32_16x16x32_bf16 v[2:5], v[180:183], v[212:215], v[2:5]
	s_barrier
; #define PG8_STAGE(bufoff, gbase, voff) do { _Pragma("unroll") for (int _i = 0; _i < 2; ++_i) \
;         __builtin_amdgcn_global_load_lds((const unsigned*)((const char*)(gbase) + (voff)[_i]), (PG8_LAS unsigned*)(lds + (bufoff) + ldsw + _i * 8192), 16, 0, 0); } while (0)
; #define PG8_LDA(dst, b, h) do { _Pragma("unroll") for (int m = 0; m < 4; ++m) _Pragma("unroll") for (int k = 0; k < 2; ++k) dst[m][k] = *(const PG8_LAS bf16x8*)(lds + PG8_SA(b, h) + aoff + m * 2048 + k * 1024); } while (0)
; #define PG8_LDB(dst, b, h) do { _Pragma("unroll") for (int n = 0; n < 2; ++n) _Pragma("unroll") for (int k = 0; k < 2; ++k) dst[n][k] = *(const PG8_LAS bf16x8*)(lds + PG8_SB(b, h) + boff + n * 2048 + k * 1024); } while (0)
; #define PG8_MMA(ai, bj, At, Bt) do { __builtin_amdgcn_s_setprio(1); _Pragma("unroll") for (int m = 0; m < 4; ++m) _Pragma("unroll") for (int n = 0; n < 2; ++n) _Pragma("unroll") for (int k = 0; k < 2; ++k) \
;         acc[ai][bj][m][n] = __builtin_amdgcn_mfma_f32_16x16x32_bf16(Bt[n][k], At[m][k], acc[ai][bj][m][n], 0, 0, 0); __builtin_amdgcn_s_setprio(0); } while (0)
; #define PG8_WAIT_V(n) asm volatile("s_waitcnt vmcnt(" #n ")" ::: "memory")
; #define PG8_WAIT_L(n) asm volatile("s_waitcnt lgkmcnt(" #n ")" ::: "memory")
; #define PG8_BAR __builtin_amdgcn_s_barrier()
; #define PG8_SCHED __builtin_amdgcn_sched_barrier(0)
; template <class Epi, class Sched, bool ALIGN_EPI = false, bool SP2 = false>
; __device__ __forceinline__ void gemm_phase(PG8_LAS unsigned char* lds, const Gemm g, const Sched& S, const Epi& E) {
;     ...
;             PG8_LDB(B0, 1, 0); PG8_LDB(B1, 1, 1); PG8_SCHED; PG8_LDA(At, 1, 0); PG8_STAGE(PG8_SA(0, 1), a2 + hA, voffA);
;             PG8_WAIT_V(8); PG8_WAIT_L(0); PG8_BAR; PG8_MMA(0, 0, At, B0); PG8_MMA(0, 1, At, B1); PG8_BAR; PG8_SCHED;
;             PG8_LDA(At, 1, 1); PG8_STAGE(PG8_SB(1, 0), b3, voffB); PG8_STAGE(PG8_SB(1, 1), b3 + hB, voffB); PG8_STAGE(PG8_SA(1, 0), a3, voffA);
;             PG8_WAIT_V(8); PG8_WAIT_L(0); PG8_BAR; PG8_MMA(1, 0, At, B0); PG8_MMA(1, 1, At, B1); PG8_BAR; PG8_SCHED;
	s_add_i32 s18, 0, 0x18000
	v_add_u32_e32 v159, s18, v154
	s_add_i32 s19, 0, 0x1c000
	ds_read_b128 v[146:149], v159
	ds_read_b128 v[150:153], v159 offset:1024
	ds_read_b128 v[160:163], v159 offset:2048
	ds_read_b128 v[164:167], v159 offset:3072
	v_add_u32_e32 v159, s19, v154
	ds_read_b128 v[168:171], v159
	ds_read_b128 v[172:175], v159 offset:1024
	ds_read_b128 v[176:179], v159 offset:2048
	ds_read_b128 v[180:183], v159 offset:3072
	s_add_u32 s46, s46, 0x40000
	s_addc_u32 s47, s47, 0
	s_mov_b32 m0, s58
	ds_read_b128 v[184:187], v158 offset:32768
	ds_read_b128 v[188:191], v158 offset:33792
	ds_read_b128 v[192:195], v158 offset:34816
	ds_read_b128 v[196:199], v158 offset:35840
	ds_read_b128 v[200:203], v158 offset:36864
	ds_read_b128 v[204:207], v158 offset:37888
	ds_read_b128 v[208:211], v158 offset:38912
	ds_read_b128 v[212:215], v158 offset:39936
	global_load_lds_dwordx4 v136, s[46:47]
	s_mov_b32 m0, s59
	s_nop 0
	global_load_lds_dwordx4 v132, s[46:47]
	s_waitcnt vmcnt(8)
	s_waitcnt lgkmcnt(0)
	s_barrier
	s_waitcnt lgkmcnt(0)
	v_mfma_f32_16x16x32_bf16 v[126:129], v[146:149], v[184:187], v[126:129]
	v_mfma_f32_16x16x32_bf16 v[122:125], v[160:163], v[184:187], v[122:125]
	v_mfma_f32_16x16x32_bf16 v[114:117], v[146:149], v[192:195], v[114:117]
	v_mfma_f32_16x16x32_bf16 v[106:109], v[160:163], v[192:195], v[106:109]
	v_mfma_f32_16x16x32_bf16 v[98:101], v[146:149], v[200:203], v[98:101]
	v_mfma_f32_16x16x32_bf16 v[90:93], v[160:163], v[200:203], v[90:93]
	v_mfma_f32_16x16x32_bf16 v[82:85], v[146:149], v[208:211], v[82:85]
	v_mfma_f32_16x16x32_bf16 v[74:77], v[160:163], v[208:211], v[74:77]
	v_mfma_f32_16x16x32_bf16 v[126:129], v[150:153], v[188:191], v[126:129]
	v_mfma_f32_16x16x32_bf16 v[122:125], v[164:167], v[188:191], v[122:125]
	v_mfma_f32_16x16x32_bf16 v[114:117], v[150:153], v[196:199], v[114:117]
	v_mfma_f32_16x16x32_bf16 v[106:109], v[164:167], v[196:199], v[106:109]
	v_mfma_f32_16x16x32_bf16 v[98:101], v[150:153], v[204:207], v[98:101]
	v_mfma_f32_16x16x32_bf16 v[90:93], v[164:167], v[204:207], v[90:93]
	v_mfma_f32_16x16x32_bf16 v[82:85], v[150:153], v[212:215], v[82:85]
	v_mfma_f32_16x16x32_bf16 v[74:77], v[164:167], v[212:215], v[74:77]
	v_mfma_f32_16x16x32_bf16 v[118:121], v[168:171], v[184:187], v[118:121]
	v_mfma_f32_16x16x32_bf16 v[110:113], v[176:179], v[184:187], v[110:113]
	v_mfma_f32_16x16x32_bf16 v[102:105], v[168:171], v[192:195], v[102:105]
	v_mfma_f32_16x16x32_bf16 v[94:97], v[176:179], v[192:195], v[94:97]
	s_mov_b32 m0, s60
	v_mfma_f32_16x16x32_bf16 v[86:89], v[168:171], v[200:203], v[86:89]
	global_load_lds_dwordx4 v136, s[80:81]
	v_mfma_f32_16x16x32_bf16 v[78:81], v[176:179], v[200:203], v[78:81]
	s_mov_b32 m0, s61
	v_mfma_f32_16x16x32_bf16 v[70:73], v[168:171], v[208:211], v[70:73]
	global_load_lds_dwordx4 v132, s[80:81]
	v_mfma_f32_16x16x32_bf16 v[66:69], v[176:179], v[208:211], v[66:69]
	v_mfma_f32_16x16x32_bf16 v[118:121], v[172:175], v[188:191], v[118:121]
	v_mfma_f32_16x16x32_bf16 v[110:113], v[180:183], v[188:191], v[110:113]
	v_mfma_f32_16x16x32_bf16 v[102:105], v[172:175], v[196:199], v[102:105]
	v_mfma_f32_16x16x32_bf16 v[94:97], v[180:183], v[196:199], v[94:97]
	v_mfma_f32_16x16x32_bf16 v[86:89], v[172:175], v[204:207], v[86:89]
	v_mfma_f32_16x16x32_bf16 v[78:81], v[180:183], v[204:207], v[78:81]
	v_mfma_f32_16x16x32_bf16 v[70:73], v[172:175], v[212:215], v[70:73]
	v_mfma_f32_16x16x32_bf16 v[66:69], v[180:183], v[212:215], v[66:69]
	s_barrier
	s_add_i32 s18, s18, s52
	s_mov_b32 m0, s18
	ds_read_b128 v[184:187], v158 offset:49152
	ds_read_b128 v[188:191], v158 offset:50176
	ds_read_b128 v[192:195], v158 offset:51200
	ds_read_b128 v[196:199], v158 offset:52224
	ds_read_b128 v[200:203], v158 offset:53248
	ds_read_b128 v[204:207], v158 offset:54272
	ds_read_b128 v[208:211], v158 offset:55296
	ds_read_b128 v[212:215], v158 offset:56320
	global_load_lds_dwordx4 v134, s[78:79]
	s_add_i32 m0, s18, 0x2000
	s_add_u32 s44, s44, 0x40080
	s_addc_u32 s45, s45, 0
	s_add_i32 s18, s19, s52
	global_load_lds_dwordx4 v130, s[78:79]
	s_mov_b32 m0, s18
	s_nop 0
	global_load_lds_dwordx4 v134, s[44:45]
	s_add_i32 m0, s18, 0x2000
	s_nop 0
	global_load_lds_dwordx4 v130, s[44:45]
	s_waitcnt vmcnt(8)
	s_waitcnt lgkmcnt(0)
	s_barrier
	s_waitcnt lgkmcnt(0)
	v_mfma_f32_16x16x32_bf16 v[62:65], v[146:149], v[184:187], v[62:65]
	v_mfma_f32_16x16x32_bf16 v[58:61], v[160:163], v[184:187], v[58:61]
	v_mfma_f32_16x16x32_bf16 v[50:53], v[146:149], v[192:195], v[50:53]
	v_mfma_f32_16x16x32_bf16 v[42:45], v[160:163], v[192:195], v[42:45]
	v_mfma_f32_16x16x32_bf16 v[34:37], v[146:149], v[200:203], v[34:37]
	v_mfma_f32_16x16x32_bf16 v[26:29], v[160:163], v[200:203], v[26:29]
	v_mfma_f32_16x16x32_bf16 v[18:21], v[146:149], v[208:211], v[18:21]
	v_mfma_f32_16x16x32_bf16 v[10:13], v[160:163], v[208:211], v[10:13]
	v_mfma_f32_16x16x32_bf16 v[62:65], v[150:153], v[188:191], v[62:65]
	v_mfma_f32_16x16x32_bf16 v[58:61], v[164:167], v[188:191], v[58:61]
	v_mfma_f32_16x16x32_bf16 v[50:53], v[150:153], v[196:199], v[50:53]
	v_mfma_f32_16x16x32_bf16 v[42:45], v[164:167], v[196:199], v[42:45]
	v_mfma_f32_16x16x32_bf16 v[34:37], v[150:153], v[204:207], v[34:37]
	v_mfma_f32_16x16x32_bf16 v[26:29], v[164:167], v[204:207], v[26:29]
	v_mfma_f32_16x16x32_bf16 v[18:21], v[150:153], v[212:215], v[18:21]
	v_mfma_f32_16x16x32_bf16 v[10:13], v[164:167], v[212:215], v[10:13]
	v_mfma_f32_16x16x32_bf16 v[54:57], v[168:171], v[184:187], v[54:57]
	v_mfma_f32_16x16x32_bf16 v[46:49], v[176:179], v[184:187], v[46:49]
	v_mfma_f32_16x16x32_bf16 v[38:41], v[168:171], v[192:195], v[38:41]
	v_mfma_f32_16x16x32_bf16 v[30:33], v[176:179], v[192:195], v[30:33]
	v_mfma_f32_16x16x32_bf16 v[22:25], v[168:171], v[200:203], v[22:25]
	v_mfma_f32_16x16x32_bf16 v[14:17], v[176:179], v[200:203], v[14:17]
	v_mfma_f32_16x16x32_bf16 v[6:9], v[168:171], v[208:211], v[6:9]
	v_mfma_f32_16x16x32_bf16 v[2:5], v[176:179], v[208:211], v[2:5]
	v_mfma_f32_16x16x32_bf16 v[54:57], v[172:175], v[188:191], v[54:57]
	v_mfma_f32_16x16x32_bf16 v[46:49], v[180:183], v[188:191], v[46:49]
	v_mfma_f32_16x16x32_bf16 v[38:41], v[172:175], v[196:199], v[38:41]
	v_mfma_f32_16x16x32_bf16 v[30:33], v[180:183], v[196:199], v[30:33]
	v_mfma_f32_16x16x32_bf16 v[22:25], v[172:175], v[204:207], v[22:25]
	v_mfma_f32_16x16x32_bf16 v[14:17], v[180:183], v[204:207], v[14:17]
	v_mfma_f32_16x16x32_bf16 v[6:9], v[172:175], v[212:215], v[6:9]
	v_mfma_f32_16x16x32_bf16 v[2:5], v[180:183], v[212:215], v[2:5]
	s_barrier
	s_add_i32 s72, s72, 2
	s_add_u32 s42, s42, 0x100
	s_addc_u32 s43, s43, 0
	s_add_u32 s70, s70, 0x100
	s_addc_u32 s71, s71, 0
	s_cmp_gt_u32 s72, 13
	s_cbranch_scc0 .Lkt_1

; #define PG8_STAGE(bufoff, gbase, voff) do { _Pragma("unroll") for (int _i = 0; _i < 2; ++_i) \
;         __builtin_amdgcn_global_load_lds((const unsigned*)((const char*)(gbase) + (voff)[_i]), (PG8_LAS unsigned*)(lds + (bufoff) + ldsw + _i * 8192), 16, 0, 0); } while (0)
; #define PG8_LDA(dst, b, h) do { _Pragma("unroll") for (int m = 0; m < 4; ++m) _Pragma("unroll") for (int k = 0; k < 2; ++k) dst[m][k] = *(const PG8_LAS bf16x8*)(lds + PG8_SA(b, h) + aoff + m * 2048 + k * 1024); } while (0)
; #define PG8_LDB(dst, b, h) do { _Pragma("unroll") for (int n = 0; n < 2; ++n) _Pragma("unroll") for (int k = 0; k < 2; ++k) dst[n][k] = *(const PG8_LAS bf16x8*)(lds + PG8_SB(b, h) + boff + n * 2048 + k * 1024); } while (0)
; #define PG8_MMA(ai, bj, At, Bt) do { __builtin_amdgcn_s_setprio(1); _Pragma("unroll") for (int m = 0; m < 4; ++m) _Pragma("unroll") for (int n = 0; n < 2; ++n) _Pragma("unroll") for (int k = 0; k < 2; ++k) \
;         acc[ai][bj][m][n] = __builtin_amdgcn_mfma_f32_16x16x32_bf16(Bt[n][k], At[m][k], acc[ai][bj][m][n], 0, 0, 0); __builtin_amdgcn_s_setprio(0); } while (0)
; #define PG8_WAIT_V(n) asm volatile("s_waitcnt vmcnt(" #n ")" ::: "memory")
; #define PG8_WAIT_L(n) asm volatile("s_waitcnt lgkmcnt(" #n ")" ::: "memory")
; #define PG8_BAR __builtin_amdgcn_s_barrier()
; #define PG8_SCHED __builtin_amdgcn_sched_barrier(0)
; template <class Epi, class Sched, bool ALIGN_EPI = false, bool SP2 = false>
; __device__ __forceinline__ void gemm_phase(PG8_LAS unsigned char* lds, const Gemm g, const Sched& S, const Epi& E) {
;     ...
;             PG8_LDB(B0, 0, 0); PG8_LDB(B1, 0, 1); PG8_SCHED; PG8_LDA(At, 0, 0); PG8_STAGE(PG8_SA(1, 1), a1 + hA, voffA);
;             PG8_WAIT_V(8); PG8_WAIT_L(0); PG8_BAR; PG8_MMA(0, 0, At, B0); PG8_MMA(0, 1, At, B1); PG8_BAR; PG8_SCHED;
;             PG8_LDA(At, 0, 1); PG8_STAGE(PG8_SB(0, 0), b2, voffB); PG8_STAGE(PG8_SB(0, 1), b2 + hB, voffB); PG8_STAGE(PG8_SA(0, 0), a2, voffA);
;             PG8_WAIT_V(8); PG8_WAIT_L(0); PG8_BAR; PG8_MMA(1, 0, At, B0); PG8_MMA(1, 1, At, B1); PG8_BAR; PG8_SCHED;
.Lkt_2:
	ds_read_b128 v[130:133], v172
	ds_read_b128 v[134:137], v172 offset:1024
	ds_read_b128 v[138:141], v172 offset:2048
	ds_read_b128 v[142:145], v172 offset:3072
	ds_read_b128 v[162:165], v173
	ds_read_b128 v[166:169], v173 offset:1024
	ds_read_b128 v[176:179], v173 offset:2048
	ds_read_b128 v[180:183], v173 offset:3072
	s_add_u32 s18, s44, 0xfff80080
	s_addc_u32 s19, s45, -1
	s_cmp_eq_u32 s74, 28
	s_cselect_b32 s49, s25, s19
	s_cselect_b32 s48, s70, s18
	s_cselect_b32 s47, s23, s73
	s_cselect_b32 s46, s71, s72
	s_add_i32 m0, s43, 0xc000
	ds_read_b128 v[184:187], v174
	ds_read_b128 v[188:191], v174 offset:1024
	ds_read_b128 v[192:195], v174 offset:2048
	ds_read_b128 v[196:199], v174 offset:3072
	ds_read_b128 v[200:203], v174 offset:4096
	ds_read_b128 v[204:207], v174 offset:5120
	ds_read_b128 v[208:211], v174 offset:6144
	ds_read_b128 v[212:215], v174 offset:7168
	global_load_lds_dwordx4 v154, s[44:45]
	s_add_i32 m0, s43, 0xe000
	s_nop 0
	global_load_lds_dwordx4 v156, s[44:45]
	s_waitcnt vmcnt(8)
	s_waitcnt lgkmcnt(0)
	s_barrier
	s_waitcnt lgkmcnt(0)
	v_mfma_f32_16x16x32_bf16 v[126:129], v[130:133], v[184:187], v[126:129]
	v_mfma_f32_16x16x32_bf16 v[122:125], v[138:141], v[184:187], v[122:125]
	v_mfma_f32_16x16x32_bf16 v[110:113], v[130:133], v[192:195], v[110:113]
	v_mfma_f32_16x16x32_bf16 v[106:109], v[138:141], v[192:195], v[106:109]
	v_mfma_f32_16x16x32_bf16 v[94:97], v[130:133], v[200:203], v[94:97]
	v_mfma_f32_16x16x32_bf16 v[90:93], v[138:141], v[200:203], v[90:93]
	v_mfma_f32_16x16x32_bf16 v[78:81], v[130:133], v[208:211], v[78:81]
	v_mfma_f32_16x16x32_bf16 v[74:77], v[138:141], v[208:211], v[74:77]
	v_mfma_f32_16x16x32_bf16 v[126:129], v[134:137], v[188:191], v[126:129]
	v_mfma_f32_16x16x32_bf16 v[122:125], v[142:145], v[188:191], v[122:125]
	v_mfma_f32_16x16x32_bf16 v[110:113], v[134:137], v[196:199], v[110:113]
	v_mfma_f32_16x16x32_bf16 v[106:109], v[142:145], v[196:199], v[106:109]
	v_mfma_f32_16x16x32_bf16 v[94:97], v[134:137], v[204:207], v[94:97]
	v_mfma_f32_16x16x32_bf16 v[90:93], v[142:145], v[204:207], v[90:93]
	v_mfma_f32_16x16x32_bf16 v[78:81], v[134:137], v[212:215], v[78:81]
	v_mfma_f32_16x16x32_bf16 v[74:77], v[142:145], v[212:215], v[74:77]
	v_mfma_f32_16x16x32_bf16 v[118:121], v[162:165], v[184:187], v[118:121]
	v_mfma_f32_16x16x32_bf16 v[114:117], v[176:179], v[184:187], v[114:117]
	v_mfma_f32_16x16x32_bf16 v[102:105], v[162:165], v[192:195], v[102:105]
	v_mfma_f32_16x16x32_bf16 v[98:101], v[176:179], v[192:195], v[98:101]
	s_mov_b32 m0, s43
	v_mfma_f32_16x16x32_bf16 v[86:89], v[162:165], v[200:203], v[86:89]
	global_load_lds_dwordx4 v152, s[48:49]
	v_mfma_f32_16x16x32_bf16 v[82:85], v[176:179], v[200:203], v[82:85]
	s_mov_b32 m0, s59
	v_mfma_f32_16x16x32_bf16 v[70:73], v[162:165], v[208:211], v[70:73]
	global_load_lds_dwordx4 v148, s[48:49]
	v_mfma_f32_16x16x32_bf16 v[66:69], v[176:179], v[208:211], v[66:69]
	v_mfma_f32_16x16x32_bf16 v[118:121], v[166:169], v[188:191], v[118:121]
	v_mfma_f32_16x16x32_bf16 v[114:117], v[180:183], v[188:191], v[114:117]
	v_mfma_f32_16x16x32_bf16 v[102:105], v[166:169], v[196:199], v[102:105]
	v_mfma_f32_16x16x32_bf16 v[98:101], v[180:183], v[196:199], v[98:101]
	v_mfma_f32_16x16x32_bf16 v[86:89], v[166:169], v[204:207], v[86:89]
	v_mfma_f32_16x16x32_bf16 v[82:85], v[180:183], v[204:207], v[82:85]
	v_mfma_f32_16x16x32_bf16 v[70:73], v[166:169], v[212:215], v[70:73]
	v_mfma_f32_16x16x32_bf16 v[66:69], v[180:183], v[212:215], v[66:69]
	s_barrier
	s_add_i32 s18, s66, s58
	s_add_u32 s78, s46, s16
	s_addc_u32 s79, s47, s17
	s_mov_b32 m0, s18
	ds_read_b128 v[184:187], v174 offset:16384
	ds_read_b128 v[188:191], v174 offset:17408
	ds_read_b128 v[192:195], v174 offset:18432
	ds_read_b128 v[196:199], v174 offset:19456
	ds_read_b128 v[200:203], v174 offset:20480
	ds_read_b128 v[204:207], v174 offset:21504
	ds_read_b128 v[208:211], v174 offset:22528
	ds_read_b128 v[212:215], v174 offset:23552
	global_load_lds_dwordx4 v150, s[46:47]
	s_add_i32 m0, s18, 0x2000
	s_add_u32 s76, s46, 0x80000
	s_addc_u32 s77, s47, 0
	s_add_i32 s18, s67, s58
	global_load_lds_dwordx4 v146, s[46:47]
	s_mov_b32 m0, s18
	s_nop 0
	global_load_lds_dwordx4 v150, s[76:77]
	s_add_i32 m0, s18, 0x2000
	s_nop 0
	global_load_lds_dwordx4 v146, s[76:77]
	s_add_u32 s80, s48, s16
	s_addc_u32 s81, s49, s17
	s_waitcnt vmcnt(8)
	s_waitcnt lgkmcnt(0)
	s_barrier
	s_waitcnt lgkmcnt(0)
	v_mfma_f32_16x16x32_bf16 v[62:65], v[130:133], v[184:187], v[62:65]
	v_mfma_f32_16x16x32_bf16 v[58:61], v[138:141], v[184:187], v[58:61]
	v_mfma_f32_16x16x32_bf16 v[46:49], v[130:133], v[192:195], v[46:49]
	v_mfma_f32_16x16x32_bf16 v[42:45], v[138:141], v[192:195], v[42:45]
	v_mfma_f32_16x16x32_bf16 v[30:33], v[130:133], v[200:203], v[30:33]
	v_mfma_f32_16x16x32_bf16 v[26:29], v[138:141], v[200:203], v[26:29]
	v_mfma_f32_16x16x32_bf16 v[14:17], v[130:133], v[208:211], v[14:17]
	v_mfma_f32_16x16x32_bf16 v[10:13], v[138:141], v[208:211], v[10:13]
	v_mfma_f32_16x16x32_bf16 v[62:65], v[134:137], v[188:191], v[62:65]
	v_mfma_f32_16x16x32_bf16 v[58:61], v[142:145], v[188:191], v[58:61]
	v_mfma_f32_16x16x32_bf16 v[46:49], v[134:137], v[196:199], v[46:49]
	v_mfma_f32_16x16x32_bf16 v[42:45], v[142:145], v[196:199], v[42:45]
	v_mfma_f32_16x16x32_bf16 v[30:33], v[134:137], v[204:207], v[30:33]
	v_mfma_f32_16x16x32_bf16 v[26:29], v[142:145], v[204:207], v[26:29]
	v_mfma_f32_16x16x32_bf16 v[14:17], v[134:137], v[212:215], v[14:17]
	v_mfma_f32_16x16x32_bf16 v[10:13], v[142:145], v[212:215], v[10:13]
	v_mfma_f32_16x16x32_bf16 v[54:57], v[162:165], v[184:187], v[54:57]
	v_mfma_f32_16x16x32_bf16 v[50:53], v[176:179], v[184:187], v[50:53]
	v_mfma_f32_16x16x32_bf16 v[38:41], v[162:165], v[192:195], v[38:41]
	v_mfma_f32_16x16x32_bf16 v[34:37], v[176:179], v[192:195], v[34:37]
	v_mfma_f32_16x16x32_bf16 v[22:25], v[162:165], v[200:203], v[22:25]
	v_mfma_f32_16x16x32_bf16 v[18:21], v[176:179], v[200:203], v[18:21]
	v_mfma_f32_16x16x32_bf16 v[6:9], v[162:165], v[208:211], v[6:9]
	v_mfma_f32_16x16x32_bf16 v[2:5], v[176:179], v[208:211], v[2:5]
	v_mfma_f32_16x16x32_bf16 v[54:57], v[166:169], v[188:191], v[54:57]
	v_mfma_f32_16x16x32_bf16 v[50:53], v[180:183], v[188:191], v[50:53]
	v_mfma_f32_16x16x32_bf16 v[38:41], v[166:169], v[196:199], v[38:41]
	v_mfma_f32_16x16x32_bf16 v[34:37], v[180:183], v[196:199], v[34:37]
	v_mfma_f32_16x16x32_bf16 v[22:25], v[166:169], v[204:207], v[22:25]
	v_mfma_f32_16x16x32_bf16 v[18:21], v[180:183], v[204:207], v[18:21]
	v_mfma_f32_16x16x32_bf16 v[6:9], v[166:169], v[212:215], v[6:9]
	v_mfma_f32_16x16x32_bf16 v[2:5], v[180:183], v[212:215], v[2:5]
	s_barrier
; #define PG8_STAGE(bufoff, gbase, voff) do { _Pragma("unroll") for (int _i = 0; _i < 2; ++_i) \
;         __builtin_amdgcn_global_load_lds((const unsigned*)((const char*)(gbase) + (voff)[_i]), (PG8_LAS unsigned*)(lds + (bufoff) + ldsw + _i * 8192), 16, 0, 0); } while (0)
; #define PG8_LDA(dst, b, h) do { _Pragma("unroll") for (int m = 0; m < 4; ++m) _Pragma("unroll") for (int k = 0; k < 2; ++k) dst[m][k] = *(const PG8_LAS bf16x8*)(lds + PG8_SA(b, h) + aoff + m * 2048 + k * 1024); } while (0)
; #define PG8_LDB(dst, b, h) do { _Pragma("unroll") for (int n = 0; n < 2; ++n) _Pragma("unroll") for (int k = 0; k < 2; ++k) dst[n][k] = *(const PG8_LAS bf16x8*)(lds + PG8_SB(b, h) + boff + n * 2048 + k * 1024); } while (0)
; #define PG8_MMA(ai, bj, At, Bt) do { __builtin_amdgcn_s_setprio(1); _Pragma("unroll") for (int m = 0; m < 4; ++m) _Pragma("unroll") for (int n = 0; n < 2; ++n) _Pragma("unroll") for (int k = 0; k < 2; ++k) \
;         acc[ai][bj][m][n] = __builtin_amdgcn_mfma_f32_16x16x32_bf16(Bt[n][k], At[m][k], acc[ai][bj][m][n], 0, 0, 0); __builtin_amdgcn_s_setprio(0); } while (0)
; #define PG8_WAIT_V(n) asm volatile("s_waitcnt vmcnt(" #n ")" ::: "memory")
; #define PG8_WAIT_L(n) asm volatile("s_waitcnt lgkmcnt(" #n ")" ::: "memory")
; #define PG8_BAR __builtin_amdgcn_s_barrier()
; #define PG8_SCHED __builtin_amdgcn_sched_barrier(0)
; template <class Epi, class Sched, bool ALIGN_EPI = false, bool SP2 = false>
; __device__ __forceinline__ void gemm_phase(PG8_LAS unsigned char* lds, const Gemm g, const Sched& S, const Epi& E) {
;     ...
;             PG8_LDB(B0, 1, 0); PG8_LDB(B1, 1, 1); PG8_SCHED; PG8_LDA(At, 1, 0); PG8_STAGE(PG8_SA(0, 1), a2 + hA, voffA);
;             PG8_WAIT_V(8); PG8_WAIT_L(0); PG8_BAR; PG8_MMA(0, 0, At, B0); PG8_MMA(0, 1, At, B1); PG8_BAR; PG8_SCHED;
;             PG8_LDA(At, 1, 1); PG8_STAGE(PG8_SB(1, 0), b3, voffB); PG8_STAGE(PG8_SB(1, 1), b3 + hB, voffB); PG8_STAGE(PG8_SA(1, 0), a3, voffA);
;             PG8_WAIT_V(8); PG8_WAIT_L(0); PG8_BAR; PG8_MMA(1, 0, At, B0); PG8_MMA(1, 1, At, B1); PG8_BAR; PG8_SCHED;
	s_add_i32 s18, 0, 0x18000
	s_add_i32 s19, 0, 0x1c000
	v_add_u32_e32 v142, s18, v170
	v_add_u32_e32 v175, s19, v170
	ds_read_b128 v[130:133], v142
	ds_read_b128 v[134:137], v142 offset:1024
	ds_read_b128 v[138:141], v142 offset:2048
	ds_read_b128 v[142:145], v142 offset:3072
	ds_read_b128 v[162:165], v175
	ds_read_b128 v[166:169], v175 offset:1024
	ds_read_b128 v[176:179], v175 offset:2048
	ds_read_b128 v[180:183], v175 offset:3072
	s_add_u32 s48, s48, 0x80000
	s_addc_u32 s49, s49, 0
	s_mov_b32 m0, s60
	ds_read_b128 v[184:187], v174 offset:32768
	ds_read_b128 v[188:191], v174 offset:33792
	ds_read_b128 v[192:195], v174 offset:34816
	ds_read_b128 v[196:199], v174 offset:35840
	ds_read_b128 v[200:203], v174 offset:36864
	ds_read_b128 v[204:207], v174 offset:37888
	ds_read_b128 v[208:211], v174 offset:38912
	ds_read_b128 v[212:215], v174 offset:39936
	global_load_lds_dwordx4 v152, s[48:49]
	s_mov_b32 m0, s61
	s_nop 0
	global_load_lds_dwordx4 v148, s[48:49]
	s_waitcnt vmcnt(8)
	s_waitcnt lgkmcnt(0)
	s_barrier
	s_waitcnt lgkmcnt(0)
	v_mfma_f32_16x16x32_bf16 v[126:129], v[130:133], v[184:187], v[126:129]
	v_mfma_f32_16x16x32_bf16 v[122:125], v[138:141], v[184:187], v[122:125]
	v_mfma_f32_16x16x32_bf16 v[110:113], v[130:133], v[192:195], v[110:113]
	v_mfma_f32_16x16x32_bf16 v[106:109], v[138:141], v[192:195], v[106:109]
	v_mfma_f32_16x16x32_bf16 v[94:97], v[130:133], v[200:203], v[94:97]
	v_mfma_f32_16x16x32_bf16 v[90:93], v[138:141], v[200:203], v[90:93]
	v_mfma_f32_16x16x32_bf16 v[78:81], v[130:133], v[208:211], v[78:81]
	v_mfma_f32_16x16x32_bf16 v[74:77], v[138:141], v[208:211], v[74:77]
	v_mfma_f32_16x16x32_bf16 v[126:129], v[134:137], v[188:191], v[126:129]
	v_mfma_f32_16x16x32_bf16 v[122:125], v[142:145], v[188:191], v[122:125]
	v_mfma_f32_16x16x32_bf16 v[110:113], v[134:137], v[196:199], v[110:113]
	v_mfma_f32_16x16x32_bf16 v[106:109], v[142:145], v[196:199], v[106:109]
	v_mfma_f32_16x16x32_bf16 v[94:97], v[134:137], v[204:207], v[94:97]
	v_mfma_f32_16x16x32_bf16 v[90:93], v[142:145], v[204:207], v[90:93]
	v_mfma_f32_16x16x32_bf16 v[78:81], v[134:137], v[212:215], v[78:81]
	v_mfma_f32_16x16x32_bf16 v[74:77], v[142:145], v[212:215], v[74:77]
	v_mfma_f32_16x16x32_bf16 v[118:121], v[162:165], v[184:187], v[118:121]
	v_mfma_f32_16x16x32_bf16 v[114:117], v[176:179], v[184:187], v[114:117]
	v_mfma_f32_16x16x32_bf16 v[102:105], v[162:165], v[192:195], v[102:105]
	v_mfma_f32_16x16x32_bf16 v[98:101], v[176:179], v[192:195], v[98:101]
	s_mov_b32 m0, s63
	v_mfma_f32_16x16x32_bf16 v[86:89], v[162:165], v[200:203], v[86:89]
	global_load_lds_dwordx4 v152, s[80:81]
	v_mfma_f32_16x16x32_bf16 v[82:85], v[176:179], v[200:203], v[82:85]
	s_mov_b32 m0, s64
	v_mfma_f32_16x16x32_bf16 v[70:73], v[162:165], v[208:211], v[70:73]
	global_load_lds_dwordx4 v148, s[80:81]
	v_mfma_f32_16x16x32_bf16 v[66:69], v[176:179], v[208:211], v[66:69]
	v_mfma_f32_16x16x32_bf16 v[118:121], v[166:169], v[188:191], v[118:121]
	v_mfma_f32_16x16x32_bf16 v[114:117], v[180:183], v[188:191], v[114:117]
	v_mfma_f32_16x16x32_bf16 v[102:105], v[166:169], v[196:199], v[102:105]
	v_mfma_f32_16x16x32_bf16 v[98:101], v[180:183], v[196:199], v[98:101]
	v_mfma_f32_16x16x32_bf16 v[86:89], v[166:169], v[204:207], v[86:89]
	v_mfma_f32_16x16x32_bf16 v[82:85], v[180:183], v[204:207], v[82:85]
	v_mfma_f32_16x16x32_bf16 v[70:73], v[166:169], v[212:215], v[70:73]
	v_mfma_f32_16x16x32_bf16 v[66:69], v[180:183], v[212:215], v[66:69]
	s_barrier
	s_add_i32 s18, s18, s58
	s_mov_b32 m0, s18
	ds_read_b128 v[184:187], v174 offset:49152
	ds_read_b128 v[188:191], v174 offset:50176
	ds_read_b128 v[192:195], v174 offset:51200
	ds_read_b128 v[196:199], v174 offset:52224
	ds_read_b128 v[200:203], v174 offset:53248
	ds_read_b128 v[204:207], v174 offset:54272
	ds_read_b128 v[208:211], v174 offset:55296
	ds_read_b128 v[212:215], v174 offset:56320
	global_load_lds_dwordx4 v150, s[78:79]
	s_add_i32 m0, s18, 0x2000
	s_add_u32 s46, s46, 0x80080
	s_addc_u32 s47, s47, 0
	s_add_i32 s18, s19, s58
	global_load_lds_dwordx4 v146, s[78:79]
	s_mov_b32 m0, s18
	s_nop 0
	global_load_lds_dwordx4 v150, s[46:47]
	s_add_i32 m0, s18, 0x2000
	s_nop 0
	global_load_lds_dwordx4 v146, s[46:47]
	s_waitcnt vmcnt(8)
	s_waitcnt lgkmcnt(0)
	s_barrier
	s_waitcnt lgkmcnt(0)
	v_mfma_f32_16x16x32_bf16 v[62:65], v[130:133], v[184:187], v[62:65]
	v_mfma_f32_16x16x32_bf16 v[58:61], v[138:141], v[184:187], v[58:61]
	v_mfma_f32_16x16x32_bf16 v[46:49], v[130:133], v[192:195], v[46:49]
	v_mfma_f32_16x16x32_bf16 v[42:45], v[138:141], v[192:195], v[42:45]
	v_mfma_f32_16x16x32_bf16 v[30:33], v[130:133], v[200:203], v[30:33]
	v_mfma_f32_16x16x32_bf16 v[26:29], v[138:141], v[200:203], v[26:29]
	v_mfma_f32_16x16x32_bf16 v[14:17], v[130:133], v[208:211], v[14:17]
	v_mfma_f32_16x16x32_bf16 v[10:13], v[138:141], v[208:211], v[10:13]
	v_mfma_f32_16x16x32_bf16 v[62:65], v[134:137], v[188:191], v[62:65]
	v_mfma_f32_16x16x32_bf16 v[58:61], v[142:145], v[188:191], v[58:61]
	v_mfma_f32_16x16x32_bf16 v[46:49], v[134:137], v[196:199], v[46:49]
	v_mfma_f32_16x16x32_bf16 v[42:45], v[142:145], v[196:199], v[42:45]
	v_mfma_f32_16x16x32_bf16 v[30:33], v[134:137], v[204:207], v[30:33]
	v_mfma_f32_16x16x32_bf16 v[26:29], v[142:145], v[204:207], v[26:29]
	v_mfma_f32_16x16x32_bf16 v[14:17], v[134:137], v[212:215], v[14:17]
	v_mfma_f32_16x16x32_bf16 v[10:13], v[142:145], v[212:215], v[10:13]
	v_mfma_f32_16x16x32_bf16 v[54:57], v[162:165], v[184:187], v[54:57]
	v_mfma_f32_16x16x32_bf16 v[50:53], v[176:179], v[184:187], v[50:53]
	v_mfma_f32_16x16x32_bf16 v[38:41], v[162:165], v[192:195], v[38:41]
	v_mfma_f32_16x16x32_bf16 v[34:37], v[176:179], v[192:195], v[34:37]
	v_mfma_f32_16x16x32_bf16 v[22:25], v[162:165], v[200:203], v[22:25]
	v_mfma_f32_16x16x32_bf16 v[18:21], v[176:179], v[200:203], v[18:21]
	v_mfma_f32_16x16x32_bf16 v[6:9], v[162:165], v[208:211], v[6:9]
	v_mfma_f32_16x16x32_bf16 v[2:5], v[176:179], v[208:211], v[2:5]
	v_mfma_f32_16x16x32_bf16 v[54:57], v[166:169], v[188:191], v[54:57]
	v_mfma_f32_16x16x32_bf16 v[50:53], v[180:183], v[188:191], v[50:53]
	v_mfma_f32_16x16x32_bf16 v[38:41], v[166:169], v[196:199], v[38:41]
	v_mfma_f32_16x16x32_bf16 v[34:37], v[180:183], v[196:199], v[34:37]
	v_mfma_f32_16x16x32_bf16 v[22:25], v[166:169], v[204:207], v[22:25]
	v_mfma_f32_16x16x32_bf16 v[18:21], v[180:183], v[204:207], v[18:21]
	v_mfma_f32_16x16x32_bf16 v[6:9], v[166:169], v[212:215], v[6:9]
	v_mfma_f32_16x16x32_bf16 v[2:5], v[180:183], v[212:215], v[2:5]
	s_barrier
	s_add_i32 s74, s74, 2
	s_add_u32 s44, s44, 0x100
	s_addc_u32 s45, s45, 0
	s_add_u32 s72, s72, 0x100
	s_addc_u32 s73, s73, 0
	s_cmp_gt_u32 s74, 29
	s_cbranch_scc0 .Lkt_2

; #define PG8_STAGE(bufoff, gbase, voff) do { _Pragma("unroll") for (int _i = 0; _i < 2; ++_i) \
;         __builtin_amdgcn_global_load_lds((const unsigned*)((const char*)(gbase) + (voff)[_i]), (PG8_LAS unsigned*)(lds + (bufoff) + ldsw + _i * 8192), 16, 0, 0); } while (0)
; #define PG8_LDA(dst, b, h) do { _Pragma("unroll") for (int m = 0; m < 4; ++m) _Pragma("unroll") for (int k = 0; k < 2; ++k) dst[m][k] = *(const PG8_LAS bf16x8*)(lds + PG8_SA(b, h) + aoff + m * 2048 + k * 1024); } while (0)
; #define PG8_LDB(dst, b, h) do { _Pragma("unroll") for (int n = 0; n < 2; ++n) _Pragma("unroll") for (int k = 0; k < 2; ++k) dst[n][k] = *(const PG8_LAS bf16x8*)(lds + PG8_SB(b, h) + boff + n * 2048 + k * 1024); } while (0)
; #define PG8_MMA(ai, bj, At, Bt) do { __builtin_amdgcn_s_setprio(1); _Pragma("unroll") for (int m = 0; m < 4; ++m) _Pragma("unroll") for (int n = 0; n < 2; ++n) _Pragma("unroll") for (int k = 0; k < 2; ++k) \
;         acc[ai][bj][m][n] = __builtin_amdgcn_mfma_f32_16x16x32_bf16(Bt[n][k], At[m][k], acc[ai][bj][m][n], 0, 0, 0); __builtin_amdgcn_s_setprio(0); } while (0)
; #define PG8_WAIT_V(n) asm volatile("s_waitcnt vmcnt(" #n ")" ::: "memory")
; #define PG8_WAIT_L(n) asm volatile("s_waitcnt lgkmcnt(" #n ")" ::: "memory")
; #define PG8_BAR __builtin_amdgcn_s_barrier()
; #define PG8_SCHED __builtin_amdgcn_sched_barrier(0)
; template <class Epi, class Sched, bool ALIGN_EPI = false, bool SP2 = false>
; __device__ __forceinline__ void gemm_phase(PG8_LAS unsigned char* lds, const Gemm g, const Sched& S, const Epi& E) {
;     ...
;             PG8_LDB(B0, 0, 0); PG8_LDB(B1, 0, 1); PG8_SCHED; PG8_LDA(At, 0, 0); PG8_STAGE(PG8_SA(1, 1), a1 + hA, voffA);
;             PG8_WAIT_V(8); PG8_WAIT_L(0); PG8_BAR; PG8_MMA(0, 0, At, B0); PG8_MMA(0, 1, At, B1); PG8_BAR; PG8_SCHED;
;             PG8_LDA(At, 0, 1); PG8_STAGE(PG8_SB(0, 0), b2, voffB); PG8_STAGE(PG8_SB(0, 1), b2 + hB, voffB); PG8_STAGE(PG8_SA(0, 0), a2, voffA);
;             PG8_WAIT_V(8); PG8_WAIT_L(0); PG8_BAR; PG8_MMA(1, 0, At, B0); PG8_MMA(1, 1, At, B1); PG8_BAR; PG8_SCHED;
.Lkt_3:
	ds_read_b128 v[130:133], v208
	ds_read_b128 v[134:137], v208 offset:1024
	ds_read_b128 v[138:141], v208 offset:2048
	ds_read_b128 v[142:145], v208 offset:3072
	ds_read_b128 v[146:149], v209
	ds_read_b128 v[150:153], v209 offset:1024
	ds_read_b128 v[154:157], v209 offset:2048
	ds_read_b128 v[158:161], v209 offset:3072
	s_add_u32 s18, s48, 0xfff80080
	s_addc_u32 s19, s49, -1
	s_cmp_eq_u32 s78, 28
	s_cselect_b32 s53, s41, s19
	s_cselect_b32 s52, s47, s18
	s_cselect_b32 s51, s39, s77
	s_cselect_b32 s50, s75, s76
	s_add_i32 m0, s62, 0xc000
	ds_read_b128 v[162:165], v210
	ds_read_b128 v[166:169], v210 offset:1024
	ds_read_b128 v[170:173], v210 offset:2048
	ds_read_b128 v[174:177], v210 offset:3072
	ds_read_b128 v[194:197], v210 offset:4096
	ds_read_b128 v[198:201], v210 offset:5120
	ds_read_b128 v[202:205], v210 offset:6144
	ds_read_b128 v[212:215], v210 offset:7168
	global_load_lds_dwordx4 v186, s[48:49]
	s_add_i32 m0, s62, 0xe000
	s_nop 0
	global_load_lds_dwordx4 v188, s[48:49]
	s_waitcnt vmcnt(8)
	s_waitcnt lgkmcnt(0)
	s_barrier
	s_waitcnt lgkmcnt(0)
	v_mfma_f32_16x16x32_bf16 v[126:129], v[130:133], v[162:165], v[126:129]
	v_mfma_f32_16x16x32_bf16 v[122:125], v[138:141], v[162:165], v[122:125]
	v_mfma_f32_16x16x32_bf16 v[110:113], v[130:133], v[170:173], v[110:113]
	v_mfma_f32_16x16x32_bf16 v[106:109], v[138:141], v[170:173], v[106:109]
	v_mfma_f32_16x16x32_bf16 v[94:97], v[130:133], v[194:197], v[94:97]
	v_mfma_f32_16x16x32_bf16 v[90:93], v[138:141], v[194:197], v[90:93]
	v_mfma_f32_16x16x32_bf16 v[78:81], v[130:133], v[202:205], v[78:81]
	v_mfma_f32_16x16x32_bf16 v[74:77], v[138:141], v[202:205], v[74:77]
	v_mfma_f32_16x16x32_bf16 v[126:129], v[134:137], v[166:169], v[126:129]
	v_mfma_f32_16x16x32_bf16 v[122:125], v[142:145], v[166:169], v[122:125]
	v_mfma_f32_16x16x32_bf16 v[110:113], v[134:137], v[174:177], v[110:113]
	v_mfma_f32_16x16x32_bf16 v[106:109], v[142:145], v[174:177], v[106:109]
	v_mfma_f32_16x16x32_bf16 v[94:97], v[134:137], v[198:201], v[94:97]
	v_mfma_f32_16x16x32_bf16 v[90:93], v[142:145], v[198:201], v[90:93]
	v_mfma_f32_16x16x32_bf16 v[78:81], v[134:137], v[212:215], v[78:81]
	v_mfma_f32_16x16x32_bf16 v[74:77], v[142:145], v[212:215], v[74:77]
	v_mfma_f32_16x16x32_bf16 v[118:121], v[146:149], v[162:165], v[118:121]
	v_mfma_f32_16x16x32_bf16 v[114:117], v[154:157], v[162:165], v[114:117]
	v_mfma_f32_16x16x32_bf16 v[102:105], v[146:149], v[170:173], v[102:105]
	v_mfma_f32_16x16x32_bf16 v[98:101], v[154:157], v[170:173], v[98:101]
	s_mov_b32 m0, s62
	v_mfma_f32_16x16x32_bf16 v[86:89], v[146:149], v[194:197], v[86:89]
	global_load_lds_dwordx4 v178, s[52:53]
	v_mfma_f32_16x16x32_bf16 v[82:85], v[154:157], v[194:197], v[82:85]
	s_mov_b32 m0, s63
	v_mfma_f32_16x16x32_bf16 v[70:73], v[146:149], v[202:205], v[70:73]
	global_load_lds_dwordx4 v182, s[52:53]
	v_mfma_f32_16x16x32_bf16 v[66:69], v[154:157], v[202:205], v[66:69]
	v_mfma_f32_16x16x32_bf16 v[118:121], v[150:153], v[166:169], v[118:121]
	v_mfma_f32_16x16x32_bf16 v[114:117], v[158:161], v[166:169], v[114:117]
	v_mfma_f32_16x16x32_bf16 v[102:105], v[150:153], v[174:177], v[102:105]
	v_mfma_f32_16x16x32_bf16 v[98:101], v[158:161], v[174:177], v[98:101]
	v_mfma_f32_16x16x32_bf16 v[86:89], v[150:153], v[198:201], v[86:89]
	v_mfma_f32_16x16x32_bf16 v[82:85], v[158:161], v[198:201], v[82:85]
	v_mfma_f32_16x16x32_bf16 v[70:73], v[150:153], v[212:215], v[70:73]
	v_mfma_f32_16x16x32_bf16 v[66:69], v[158:161], v[212:215], v[66:69]
	s_barrier
	s_add_i32 s18, s72, s61
	s_add_u32 s82, s50, s22
	s_addc_u32 s83, s51, s23
	s_mov_b32 m0, s18
	ds_read_b128 v[162:165], v210 offset:16384
	ds_read_b128 v[166:169], v210 offset:17408
	ds_read_b128 v[170:173], v210 offset:18432
	ds_read_b128 v[174:177], v210 offset:19456
	ds_read_b128 v[194:197], v210 offset:20480
	ds_read_b128 v[198:201], v210 offset:21504
	ds_read_b128 v[202:205], v210 offset:22528
	ds_read_b128 v[212:215], v210 offset:23552
	global_load_lds_dwordx4 v180, s[50:51]
	s_add_i32 m0, s18, 0x2000
	s_add_u32 s80, s50, 0x80000
	s_addc_u32 s81, s51, 0
	s_add_i32 s18, s73, s61
	global_load_lds_dwordx4 v184, s[50:51]
	s_mov_b32 m0, s18
	s_nop 0
	global_load_lds_dwordx4 v180, s[80:81]
	s_add_i32 m0, s18, 0x2000
	s_nop 0
	global_load_lds_dwordx4 v184, s[80:81]
	s_add_u32 s88, s52, s22
	s_addc_u32 s89, s53, s23
	s_waitcnt vmcnt(8)
	s_waitcnt lgkmcnt(0)
	s_barrier
	s_waitcnt lgkmcnt(0)
	v_mfma_f32_16x16x32_bf16 v[62:65], v[130:133], v[162:165], v[62:65]
	v_mfma_f32_16x16x32_bf16 v[58:61], v[138:141], v[162:165], v[58:61]
	v_mfma_f32_16x16x32_bf16 v[46:49], v[130:133], v[170:173], v[46:49]
	v_mfma_f32_16x16x32_bf16 v[42:45], v[138:141], v[170:173], v[42:45]
	v_mfma_f32_16x16x32_bf16 v[30:33], v[130:133], v[194:197], v[30:33]
	v_mfma_f32_16x16x32_bf16 v[26:29], v[138:141], v[194:197], v[26:29]
	v_mfma_f32_16x16x32_bf16 v[14:17], v[130:133], v[202:205], v[14:17]
	v_mfma_f32_16x16x32_bf16 v[10:13], v[138:141], v[202:205], v[10:13]
	v_mfma_f32_16x16x32_bf16 v[62:65], v[134:137], v[166:169], v[62:65]
	v_mfma_f32_16x16x32_bf16 v[58:61], v[142:145], v[166:169], v[58:61]
	v_mfma_f32_16x16x32_bf16 v[46:49], v[134:137], v[174:177], v[46:49]
	v_mfma_f32_16x16x32_bf16 v[42:45], v[142:145], v[174:177], v[42:45]
	v_mfma_f32_16x16x32_bf16 v[30:33], v[134:137], v[198:201], v[30:33]
	v_mfma_f32_16x16x32_bf16 v[26:29], v[142:145], v[198:201], v[26:29]
	v_mfma_f32_16x16x32_bf16 v[14:17], v[134:137], v[212:215], v[14:17]
	v_mfma_f32_16x16x32_bf16 v[10:13], v[142:145], v[212:215], v[10:13]
	v_mfma_f32_16x16x32_bf16 v[54:57], v[146:149], v[162:165], v[54:57]
	v_mfma_f32_16x16x32_bf16 v[50:53], v[154:157], v[162:165], v[50:53]
	v_mfma_f32_16x16x32_bf16 v[38:41], v[146:149], v[170:173], v[38:41]
	v_mfma_f32_16x16x32_bf16 v[34:37], v[154:157], v[170:173], v[34:37]
	v_mfma_f32_16x16x32_bf16 v[22:25], v[146:149], v[194:197], v[22:25]
	v_mfma_f32_16x16x32_bf16 v[18:21], v[154:157], v[194:197], v[18:21]
	v_mfma_f32_16x16x32_bf16 v[6:9], v[146:149], v[202:205], v[6:9]
	v_mfma_f32_16x16x32_bf16 v[2:5], v[154:157], v[202:205], v[2:5]
	v_mfma_f32_16x16x32_bf16 v[54:57], v[150:153], v[166:169], v[54:57]
	v_mfma_f32_16x16x32_bf16 v[50:53], v[158:161], v[166:169], v[50:53]
	v_mfma_f32_16x16x32_bf16 v[38:41], v[150:153], v[174:177], v[38:41]
	v_mfma_f32_16x16x32_bf16 v[34:37], v[158:161], v[174:177], v[34:37]
	v_mfma_f32_16x16x32_bf16 v[22:25], v[150:153], v[198:201], v[22:25]
	v_mfma_f32_16x16x32_bf16 v[18:21], v[158:161], v[198:201], v[18:21]
	v_mfma_f32_16x16x32_bf16 v[6:9], v[150:153], v[212:215], v[6:9]
	v_mfma_f32_16x16x32_bf16 v[2:5], v[158:161], v[212:215], v[2:5]
	s_barrier
; #define PG8_STAGE(bufoff, gbase, voff) do { _Pragma("unroll") for (int _i = 0; _i < 2; ++_i) \
;         __builtin_amdgcn_global_load_lds((const unsigned*)((const char*)(gbase) + (voff)[_i]), (PG8_LAS unsigned*)(lds + (bufoff) + ldsw + _i * 8192), 16, 0, 0); } while (0)
; #define PG8_LDA(dst, b, h) do { _Pragma("unroll") for (int m = 0; m < 4; ++m) _Pragma("unroll") for (int k = 0; k < 2; ++k) dst[m][k] = *(const PG8_LAS bf16x8*)(lds + PG8_SA(b, h) + aoff + m * 2048 + k * 1024); } while (0)
; #define PG8_LDB(dst, b, h) do { _Pragma("unroll") for (int n = 0; n < 2; ++n) _Pragma("unroll") for (int k = 0; k < 2; ++k) dst[n][k] = *(const PG8_LAS bf16x8*)(lds + PG8_SB(b, h) + boff + n * 2048 + k * 1024); } while (0)
; #define PG8_MMA(ai, bj, At, Bt) do { __builtin_amdgcn_s_setprio(1); _Pragma("unroll") for (int m = 0; m < 4; ++m) _Pragma("unroll") for (int n = 0; n < 2; ++n) _Pragma("unroll") for (int k = 0; k < 2; ++k) \
;         acc[ai][bj][m][n] = __builtin_amdgcn_mfma_f32_16x16x32_bf16(Bt[n][k], At[m][k], acc[ai][bj][m][n], 0, 0, 0); __builtin_amdgcn_s_setprio(0); } while (0)
; #define PG8_WAIT_V(n) asm volatile("s_waitcnt vmcnt(" #n ")" ::: "memory")
; #define PG8_WAIT_L(n) asm volatile("s_waitcnt lgkmcnt(" #n ")" ::: "memory")
; #define PG8_BAR __builtin_amdgcn_s_barrier()
; #define PG8_SCHED __builtin_amdgcn_sched_barrier(0)
; template <class Epi, class Sched, bool ALIGN_EPI = false, bool SP2 = false>
; __device__ __forceinline__ void gemm_phase(PG8_LAS unsigned char* lds, const Gemm g, const Sched& S, const Epi& E) {
;     ...
;             PG8_LDB(B0, 1, 0); PG8_LDB(B1, 1, 1); PG8_SCHED; PG8_LDA(At, 1, 0); PG8_STAGE(PG8_SA(0, 1), a2 + hA, voffA);
;             PG8_WAIT_V(8); PG8_WAIT_L(0); PG8_BAR; PG8_MMA(0, 0, At, B0); PG8_MMA(0, 1, At, B1); PG8_BAR; PG8_SCHED;
;             PG8_LDA(At, 1, 1); PG8_STAGE(PG8_SB(1, 0), b3, voffB); PG8_STAGE(PG8_SB(1, 1), b3 + hB, voffB); PG8_STAGE(PG8_SA(1, 0), a3, voffA);
;             PG8_WAIT_V(8); PG8_WAIT_L(0); PG8_BAR; PG8_MMA(1, 0, At, B0); PG8_MMA(1, 1, At, B1); PG8_BAR; PG8_SCHED;
	s_add_i32 s18, 0, 0x18000
	s_add_i32 s19, 0, 0x1c000
	v_add_u32_e32 v142, s18, v206
	v_add_u32_e32 v158, s19, v206
	ds_read_b128 v[130:133], v142
	ds_read_b128 v[134:137], v142 offset:1024
	ds_read_b128 v[138:141], v142 offset:2048
	ds_read_b128 v[142:145], v142 offset:3072
	ds_read_b128 v[146:149], v158
	ds_read_b128 v[150:153], v158 offset:1024
	ds_read_b128 v[154:157], v158 offset:2048
	ds_read_b128 v[158:161], v158 offset:3072
	s_add_u32 s52, s52, 0x80000
	s_addc_u32 s53, s53, 0
	s_mov_b32 m0, s64
	ds_read_b128 v[162:165], v210 offset:32768
	ds_read_b128 v[166:169], v210 offset:33792
	ds_read_b128 v[170:173], v210 offset:34816
	ds_read_b128 v[174:177], v210 offset:35840
	ds_read_b128 v[194:197], v210 offset:36864
	ds_read_b128 v[198:201], v210 offset:37888
	ds_read_b128 v[202:205], v210 offset:38912
	ds_read_b128 v[212:215], v210 offset:39936
	global_load_lds_dwordx4 v178, s[52:53]
	s_mov_b32 m0, s65
	s_nop 0
	global_load_lds_dwordx4 v182, s[52:53]
	s_waitcnt vmcnt(8)
	s_waitcnt lgkmcnt(0)
	s_barrier
	s_waitcnt lgkmcnt(0)
	v_mfma_f32_16x16x32_bf16 v[126:129], v[130:133], v[162:165], v[126:129]
	v_mfma_f32_16x16x32_bf16 v[122:125], v[138:141], v[162:165], v[122:125]
	v_mfma_f32_16x16x32_bf16 v[110:113], v[130:133], v[170:173], v[110:113]
	v_mfma_f32_16x16x32_bf16 v[106:109], v[138:141], v[170:173], v[106:109]
	v_mfma_f32_16x16x32_bf16 v[94:97], v[130:133], v[194:197], v[94:97]
	v_mfma_f32_16x16x32_bf16 v[90:93], v[138:141], v[194:197], v[90:93]
	v_mfma_f32_16x16x32_bf16 v[78:81], v[130:133], v[202:205], v[78:81]
	v_mfma_f32_16x16x32_bf16 v[74:77], v[138:141], v[202:205], v[74:77]
	v_mfma_f32_16x16x32_bf16 v[126:129], v[134:137], v[166:169], v[126:129]
	v_mfma_f32_16x16x32_bf16 v[122:125], v[142:145], v[166:169], v[122:125]
	v_mfma_f32_16x16x32_bf16 v[110:113], v[134:137], v[174:177], v[110:113]
	v_mfma_f32_16x16x32_bf16 v[106:109], v[142:145], v[174:177], v[106:109]
	v_mfma_f32_16x16x32_bf16 v[94:97], v[134:137], v[198:201], v[94:97]
	v_mfma_f32_16x16x32_bf16 v[90:93], v[142:145], v[198:201], v[90:93]
	v_mfma_f32_16x16x32_bf16 v[78:81], v[134:137], v[212:215], v[78:81]
	v_mfma_f32_16x16x32_bf16 v[74:77], v[142:145], v[212:215], v[74:77]
	v_mfma_f32_16x16x32_bf16 v[118:121], v[146:149], v[162:165], v[118:121]
	v_mfma_f32_16x16x32_bf16 v[114:117], v[154:157], v[162:165], v[114:117]
	v_mfma_f32_16x16x32_bf16 v[102:105], v[146:149], v[170:173], v[102:105]
	v_mfma_f32_16x16x32_bf16 v[98:101], v[154:157], v[170:173], v[98:101]
	s_mov_b32 m0, s69
	v_mfma_f32_16x16x32_bf16 v[86:89], v[146:149], v[194:197], v[86:89]
	global_load_lds_dwordx4 v178, s[88:89]
	v_mfma_f32_16x16x32_bf16 v[82:85], v[154:157], v[194:197], v[82:85]
	s_mov_b32 m0, s70
	v_mfma_f32_16x16x32_bf16 v[70:73], v[146:149], v[202:205], v[70:73]
	global_load_lds_dwordx4 v182, s[88:89]
	v_mfma_f32_16x16x32_bf16 v[66:69], v[154:157], v[202:205], v[66:69]
	v_mfma_f32_16x16x32_bf16 v[118:121], v[150:153], v[166:169], v[118:121]
	v_mfma_f32_16x16x32_bf16 v[114:117], v[158:161], v[166:169], v[114:117]
	v_mfma_f32_16x16x32_bf16 v[102:105], v[150:153], v[174:177], v[102:105]
	v_mfma_f32_16x16x32_bf16 v[98:101], v[158:161], v[174:177], v[98:101]
	v_mfma_f32_16x16x32_bf16 v[86:89], v[150:153], v[198:201], v[86:89]
	v_mfma_f32_16x16x32_bf16 v[82:85], v[158:161], v[198:201], v[82:85]
	v_mfma_f32_16x16x32_bf16 v[70:73], v[150:153], v[212:215], v[70:73]
	v_mfma_f32_16x16x32_bf16 v[66:69], v[158:161], v[212:215], v[66:69]
	s_barrier
	s_add_i32 s18, s18, s61
	s_mov_b32 m0, s18
	ds_read_b128 v[162:165], v210 offset:49152
	ds_read_b128 v[166:169], v210 offset:50176
	ds_read_b128 v[170:173], v210 offset:51200
	ds_read_b128 v[174:177], v210 offset:52224
	ds_read_b128 v[194:197], v210 offset:53248
	ds_read_b128 v[198:201], v210 offset:54272
	ds_read_b128 v[202:205], v210 offset:55296
	ds_read_b128 v[212:215], v210 offset:56320
	global_load_lds_dwordx4 v180, s[82:83]
	s_add_i32 m0, s18, 0x2000
	s_add_u32 s50, s50, 0x80080
	s_addc_u32 s51, s51, 0
	s_add_i32 s18, s19, s61
	global_load_lds_dwordx4 v184, s[82:83]
	s_mov_b32 m0, s18
	s_nop 0
	global_load_lds_dwordx4 v180, s[50:51]
	s_add_i32 m0, s18, 0x2000
	s_nop 0
	global_load_lds_dwordx4 v184, s[50:51]
	s_waitcnt vmcnt(8)
	s_waitcnt lgkmcnt(0)
	s_barrier
	s_waitcnt lgkmcnt(0)
	v_mfma_f32_16x16x32_bf16 v[62:65], v[130:133], v[162:165], v[62:65]
	v_mfma_f32_16x16x32_bf16 v[58:61], v[138:141], v[162:165], v[58:61]
	v_mfma_f32_16x16x32_bf16 v[46:49], v[130:133], v[170:173], v[46:49]
	v_mfma_f32_16x16x32_bf16 v[42:45], v[138:141], v[170:173], v[42:45]
	v_mfma_f32_16x16x32_bf16 v[30:33], v[130:133], v[194:197], v[30:33]
	v_mfma_f32_16x16x32_bf16 v[26:29], v[138:141], v[194:197], v[26:29]
	v_mfma_f32_16x16x32_bf16 v[14:17], v[130:133], v[202:205], v[14:17]
	v_mfma_f32_16x16x32_bf16 v[10:13], v[138:141], v[202:205], v[10:13]
	v_mfma_f32_16x16x32_bf16 v[62:65], v[134:137], v[166:169], v[62:65]
	v_mfma_f32_16x16x32_bf16 v[58:61], v[142:145], v[166:169], v[58:61]
	v_mfma_f32_16x16x32_bf16 v[46:49], v[134:137], v[174:177], v[46:49]
	v_mfma_f32_16x16x32_bf16 v[42:45], v[142:145], v[174:177], v[42:45]
	v_mfma_f32_16x16x32_bf16 v[30:33], v[134:137], v[198:201], v[30:33]
	v_mfma_f32_16x16x32_bf16 v[26:29], v[142:145], v[198:201], v[26:29]
	v_mfma_f32_16x16x32_bf16 v[14:17], v[134:137], v[212:215], v[14:17]
	v_mfma_f32_16x16x32_bf16 v[10:13], v[142:145], v[212:215], v[10:13]
	v_mfma_f32_16x16x32_bf16 v[54:57], v[146:149], v[162:165], v[54:57]
	v_mfma_f32_16x16x32_bf16 v[50:53], v[154:157], v[162:165], v[50:53]
	v_mfma_f32_16x16x32_bf16 v[38:41], v[146:149], v[170:173], v[38:41]
	v_mfma_f32_16x16x32_bf16 v[34:37], v[154:157], v[170:173], v[34:37]
	v_mfma_f32_16x16x32_bf16 v[22:25], v[146:149], v[194:197], v[22:25]
	v_mfma_f32_16x16x32_bf16 v[18:21], v[154:157], v[194:197], v[18:21]
	v_mfma_f32_16x16x32_bf16 v[6:9], v[146:149], v[202:205], v[6:9]
	v_mfma_f32_16x16x32_bf16 v[2:5], v[154:157], v[202:205], v[2:5]
	v_mfma_f32_16x16x32_bf16 v[54:57], v[150:153], v[166:169], v[54:57]
	v_mfma_f32_16x16x32_bf16 v[50:53], v[158:161], v[166:169], v[50:53]
	v_mfma_f32_16x16x32_bf16 v[38:41], v[150:153], v[174:177], v[38:41]
	v_mfma_f32_16x16x32_bf16 v[34:37], v[158:161], v[174:177], v[34:37]
	v_mfma_f32_16x16x32_bf16 v[22:25], v[150:153], v[198:201], v[22:25]
	v_mfma_f32_16x16x32_bf16 v[18:21], v[158:161], v[198:201], v[18:21]
	v_mfma_f32_16x16x32_bf16 v[6:9], v[150:153], v[212:215], v[6:9]
	v_mfma_f32_16x16x32_bf16 v[2:5], v[158:161], v[212:215], v[2:5]
	s_barrier
	s_add_i32 s78, s78, 2
	s_add_u32 s48, s48, 0x100
	s_addc_u32 s49, s49, 0
	s_add_u32 s76, s76, 0x100
	s_addc_u32 s77, s77, 0
	s_cmp_gt_u32 s78, 29
	s_cbranch_scc0 .Lkt_3

; #define PG8_STAGE(bufoff, gbase, voff) do { _Pragma("unroll") for (int _i = 0; _i < 2; ++_i) \
;         __builtin_amdgcn_global_load_lds((const unsigned*)((const char*)(gbase) + (voff)[_i]), (PG8_LAS unsigned*)(lds + (bufoff) + ldsw + _i * 8192), 16, 0, 0); } while (0)
; #define PG8_LDA(dst, b, h) do { _Pragma("unroll") for (int m = 0; m < 4; ++m) _Pragma("unroll") for (int k = 0; k < 2; ++k) dst[m][k] = *(const PG8_LAS bf16x8*)(lds + PG8_SA(b, h) + aoff + m * 2048 + k * 1024); } while (0)
; #define PG8_LDB(dst, b, h) do { _Pragma("unroll") for (int n = 0; n < 2; ++n) _Pragma("unroll") for (int k = 0; k < 2; ++k) dst[n][k] = *(const PG8_LAS bf16x8*)(lds + PG8_SB(b, h) + boff + n * 2048 + k * 1024); } while (0)
; #define PG8_MMA(ai, bj, At, Bt) do { __builtin_amdgcn_s_setprio(1); _Pragma("unroll") for (int m = 0; m < 4; ++m) _Pragma("unroll") for (int n = 0; n < 2; ++n) _Pragma("unroll") for (int k = 0; k < 2; ++k) \
;         acc[ai][bj][m][n] = __builtin_amdgcn_mfma_f32_16x16x32_bf16(Bt[n][k], At[m][k], acc[ai][bj][m][n], 0, 0, 0); __builtin_amdgcn_s_setprio(0); } while (0)
; #define PG8_WAIT_V(n) asm volatile("s_waitcnt vmcnt(" #n ")" ::: "memory")
; #define PG8_WAIT_L(n) asm volatile("s_waitcnt lgkmcnt(" #n ")" ::: "memory")
; #define PG8_BAR __builtin_amdgcn_s_barrier()
; #define PG8_SCHED __builtin_amdgcn_sched_barrier(0)
; template <class Epi, class Sched, bool ALIGN_EPI = false, bool SP2 = false>
; __device__ __forceinline__ void gemm_phase(PG8_LAS unsigned char* lds, const Gemm g, const Sched& S, const Epi& E) {
;     ...
;             PG8_LDB(B0, 0, 0); PG8_LDB(B1, 0, 1); PG8_SCHED; PG8_LDA(At, 0, 0); PG8_STAGE(PG8_SA(1, 1), a1 + hA, voffA);
;             PG8_WAIT_V(8); PG8_WAIT_L(0); PG8_BAR; PG8_MMA(0, 0, At, B0); PG8_MMA(0, 1, At, B1); PG8_BAR; PG8_SCHED;
;             PG8_LDA(At, 0, 1); PG8_STAGE(PG8_SB(0, 0), b2, voffB); PG8_STAGE(PG8_SB(0, 1), b2 + hB, voffB); PG8_STAGE(PG8_SA(0, 0), a2, voffA);
;             PG8_WAIT_V(8); PG8_WAIT_L(0); PG8_BAR; PG8_MMA(1, 0, At, B0); PG8_MMA(1, 1, At, B1); PG8_BAR; PG8_SCHED;
.Lkt_4:
	ds_read_b128 v[148:151], v169
	ds_read_b128 v[152:155], v169 offset:1024
	ds_read_b128 v[156:159], v169 offset:2048
	ds_read_b128 v[160:163], v169 offset:3072
	ds_read_b128 v[180:183], v171
	ds_read_b128 v[184:187], v171 offset:1024
	ds_read_b128 v[188:191], v171 offset:2048
	ds_read_b128 v[192:195], v171 offset:3072
	s_add_u32 s18, s8, 0xfff80080
	s_addc_u32 s19, s9, -1
	s_cmp_eq_u32 s72, 28
	s_cselect_b32 s45, s1, s19
	s_cselect_b32 s44, s37, s18
	s_cselect_b32 s43, s25, s71
	s_cselect_b32 s42, s69, s70
	s_add_i32 m0, s51, 0xc000
	ds_read_b128 v[196:199], v173
	ds_read_b128 v[200:203], v173 offset:1024
	ds_read_b128 v[204:207], v173 offset:2048
	ds_read_b128 v[208:211], v173 offset:3072
	ds_read_b128 v[212:215], v173 offset:4096
	ds_read_b128 v[216:219], v173 offset:5120
	ds_read_b128 v[224:227], v173 offset:6144
	ds_read_b128 v[228:231], v173 offset:7168
	global_load_lds_dwordx4 v140, s[8:9]
	s_add_i32 m0, s51, 0xe000
	s_nop 0
	global_load_lds_dwordx4 v142, s[8:9]
	s_waitcnt vmcnt(8)
	s_waitcnt lgkmcnt(0)
	s_barrier
	s_waitcnt lgkmcnt(0)
	v_mfma_f32_16x16x32_bf16 v[126:129], v[148:151], v[196:199], v[126:129]
	v_mfma_f32_16x16x32_bf16 v[122:125], v[156:159], v[196:199], v[122:125]
	v_mfma_f32_16x16x32_bf16 v[110:113], v[148:151], v[204:207], v[110:113]
	v_mfma_f32_16x16x32_bf16 v[106:109], v[156:159], v[204:207], v[106:109]
	v_mfma_f32_16x16x32_bf16 v[94:97], v[148:151], v[212:215], v[94:97]
	v_mfma_f32_16x16x32_bf16 v[90:93], v[156:159], v[212:215], v[90:93]
	v_mfma_f32_16x16x32_bf16 v[78:81], v[148:151], v[224:227], v[78:81]
	v_mfma_f32_16x16x32_bf16 v[74:77], v[156:159], v[224:227], v[74:77]
	v_mfma_f32_16x16x32_bf16 v[126:129], v[152:155], v[200:203], v[126:129]
	v_mfma_f32_16x16x32_bf16 v[122:125], v[160:163], v[200:203], v[122:125]
	v_mfma_f32_16x16x32_bf16 v[110:113], v[152:155], v[208:211], v[110:113]
	v_mfma_f32_16x16x32_bf16 v[106:109], v[160:163], v[208:211], v[106:109]
	v_mfma_f32_16x16x32_bf16 v[94:97], v[152:155], v[216:219], v[94:97]
	v_mfma_f32_16x16x32_bf16 v[90:93], v[160:163], v[216:219], v[90:93]
	v_mfma_f32_16x16x32_bf16 v[78:81], v[152:155], v[228:231], v[78:81]
	v_mfma_f32_16x16x32_bf16 v[74:77], v[160:163], v[228:231], v[74:77]
	v_mfma_f32_16x16x32_bf16 v[118:121], v[180:183], v[196:199], v[118:121]
	v_mfma_f32_16x16x32_bf16 v[114:117], v[188:191], v[196:199], v[114:117]
	v_mfma_f32_16x16x32_bf16 v[102:105], v[180:183], v[204:207], v[102:105]
	v_mfma_f32_16x16x32_bf16 v[98:101], v[188:191], v[204:207], v[98:101]
	s_mov_b32 m0, s51
	v_mfma_f32_16x16x32_bf16 v[86:89], v[180:183], v[212:215], v[86:89]
	global_load_lds_dwordx4 v136, s[44:45]
	v_mfma_f32_16x16x32_bf16 v[82:85], v[188:191], v[212:215], v[82:85]
	s_mov_b32 m0, s52
	v_mfma_f32_16x16x32_bf16 v[70:73], v[180:183], v[224:227], v[70:73]
	global_load_lds_dwordx4 v132, s[44:45]
	v_mfma_f32_16x16x32_bf16 v[66:69], v[188:191], v[224:227], v[66:69]
	v_mfma_f32_16x16x32_bf16 v[118:121], v[184:187], v[200:203], v[118:121]
	v_mfma_f32_16x16x32_bf16 v[114:117], v[192:195], v[200:203], v[114:117]
	v_mfma_f32_16x16x32_bf16 v[102:105], v[184:187], v[208:211], v[102:105]
	v_mfma_f32_16x16x32_bf16 v[98:101], v[192:195], v[208:211], v[98:101]
	v_mfma_f32_16x16x32_bf16 v[86:89], v[184:187], v[216:219], v[86:89]
	v_mfma_f32_16x16x32_bf16 v[82:85], v[192:195], v[216:219], v[82:85]
	v_mfma_f32_16x16x32_bf16 v[70:73], v[184:187], v[228:231], v[70:73]
	v_mfma_f32_16x16x32_bf16 v[66:69], v[192:195], v[228:231], v[66:69]
	s_barrier
	s_add_i32 s18, s63, s49
	s_add_u32 s76, s42, s20
	s_addc_u32 s77, s43, s21
	s_mov_b32 m0, s18
	ds_read_b128 v[196:199], v173 offset:16384
	ds_read_b128 v[200:203], v173 offset:17408
	ds_read_b128 v[204:207], v173 offset:18432
	ds_read_b128 v[208:211], v173 offset:19456
	ds_read_b128 v[212:215], v173 offset:20480
	ds_read_b128 v[216:219], v173 offset:21504
	ds_read_b128 v[224:227], v173 offset:22528
	ds_read_b128 v[228:231], v173 offset:23552
	global_load_lds_dwordx4 v134, s[42:43]
	s_add_i32 m0, s18, 0x2000
	s_add_u32 s74, s42, 0x80000
	s_addc_u32 s75, s43, 0
	s_add_i32 s18, s64, s49
	global_load_lds_dwordx4 v130, s[42:43]
	s_mov_b32 m0, s18
	s_nop 0
	global_load_lds_dwordx4 v134, s[74:75]
	s_add_i32 m0, s18, 0x2000
	s_nop 0
	global_load_lds_dwordx4 v130, s[74:75]
	s_add_u32 s78, s44, s20
	s_addc_u32 s79, s45, s21
	s_waitcnt vmcnt(8)
	s_waitcnt lgkmcnt(0)
	s_barrier
	s_waitcnt lgkmcnt(0)
	v_mfma_f32_16x16x32_bf16 v[62:65], v[148:151], v[196:199], v[62:65]
	v_mfma_f32_16x16x32_bf16 v[58:61], v[156:159], v[196:199], v[58:61]
	v_mfma_f32_16x16x32_bf16 v[46:49], v[148:151], v[204:207], v[46:49]
	v_mfma_f32_16x16x32_bf16 v[42:45], v[156:159], v[204:207], v[42:45]
	v_mfma_f32_16x16x32_bf16 v[30:33], v[148:151], v[212:215], v[30:33]
	v_mfma_f32_16x16x32_bf16 v[26:29], v[156:159], v[212:215], v[26:29]
	v_mfma_f32_16x16x32_bf16 v[14:17], v[148:151], v[224:227], v[14:17]
	v_mfma_f32_16x16x32_bf16 v[10:13], v[156:159], v[224:227], v[10:13]
	v_mfma_f32_16x16x32_bf16 v[62:65], v[152:155], v[200:203], v[62:65]
	v_mfma_f32_16x16x32_bf16 v[58:61], v[160:163], v[200:203], v[58:61]
	v_mfma_f32_16x16x32_bf16 v[46:49], v[152:155], v[208:211], v[46:49]
	v_mfma_f32_16x16x32_bf16 v[42:45], v[160:163], v[208:211], v[42:45]
	v_mfma_f32_16x16x32_bf16 v[30:33], v[152:155], v[216:219], v[30:33]
	v_mfma_f32_16x16x32_bf16 v[26:29], v[160:163], v[216:219], v[26:29]
	v_mfma_f32_16x16x32_bf16 v[14:17], v[152:155], v[228:231], v[14:17]
	v_mfma_f32_16x16x32_bf16 v[10:13], v[160:163], v[228:231], v[10:13]
	v_mfma_f32_16x16x32_bf16 v[54:57], v[180:183], v[196:199], v[54:57]
	v_mfma_f32_16x16x32_bf16 v[50:53], v[188:191], v[196:199], v[50:53]
	v_mfma_f32_16x16x32_bf16 v[38:41], v[180:183], v[204:207], v[38:41]
	v_mfma_f32_16x16x32_bf16 v[34:37], v[188:191], v[204:207], v[34:37]
	v_mfma_f32_16x16x32_bf16 v[22:25], v[180:183], v[212:215], v[22:25]
	v_mfma_f32_16x16x32_bf16 v[18:21], v[188:191], v[212:215], v[18:21]
	v_mfma_f32_16x16x32_bf16 v[6:9], v[180:183], v[224:227], v[6:9]
	v_mfma_f32_16x16x32_bf16 v[2:5], v[188:191], v[224:227], v[2:5]
	v_mfma_f32_16x16x32_bf16 v[54:57], v[184:187], v[200:203], v[54:57]
	v_mfma_f32_16x16x32_bf16 v[50:53], v[192:195], v[200:203], v[50:53]
	v_mfma_f32_16x16x32_bf16 v[38:41], v[184:187], v[208:211], v[38:41]
	v_mfma_f32_16x16x32_bf16 v[34:37], v[192:195], v[208:211], v[34:37]
	v_mfma_f32_16x16x32_bf16 v[22:25], v[184:187], v[216:219], v[22:25]
	v_mfma_f32_16x16x32_bf16 v[18:21], v[192:195], v[216:219], v[18:21]
	v_mfma_f32_16x16x32_bf16 v[6:9], v[184:187], v[228:231], v[6:9]
	v_mfma_f32_16x16x32_bf16 v[2:5], v[192:195], v[228:231], v[2:5]
	s_barrier
; #define PG8_STAGE(bufoff, gbase, voff) do { _Pragma("unroll") for (int _i = 0; _i < 2; ++_i) \
;         __builtin_amdgcn_global_load_lds((const unsigned*)((const char*)(gbase) + (voff)[_i]), (PG8_LAS unsigned*)(lds + (bufoff) + ldsw + _i * 8192), 16, 0, 0); } while (0)
; #define PG8_LDA(dst, b, h) do { _Pragma("unroll") for (int m = 0; m < 4; ++m) _Pragma("unroll") for (int k = 0; k < 2; ++k) dst[m][k] = *(const PG8_LAS bf16x8*)(lds + PG8_SA(b, h) + aoff + m * 2048 + k * 1024); } while (0)
; #define PG8_LDB(dst, b, h) do { _Pragma("unroll") for (int n = 0; n < 2; ++n) _Pragma("unroll") for (int k = 0; k < 2; ++k) dst[n][k] = *(const PG8_LAS bf16x8*)(lds + PG8_SB(b, h) + boff + n * 2048 + k * 1024); } while (0)
; #define PG8_MMA(ai, bj, At, Bt) do { __builtin_amdgcn_s_setprio(1); _Pragma("unroll") for (int m = 0; m < 4; ++m) _Pragma("unroll") for (int n = 0; n < 2; ++n) _Pragma("unroll") for (int k = 0; k < 2; ++k) \
;         acc[ai][bj][m][n] = __builtin_amdgcn_mfma_f32_16x16x32_bf16(Bt[n][k], At[m][k], acc[ai][bj][m][n], 0, 0, 0); __builtin_amdgcn_s_setprio(0); } while (0)
; #define PG8_WAIT_V(n) asm volatile("s_waitcnt vmcnt(" #n ")" ::: "memory")
; #define PG8_WAIT_L(n) asm volatile("s_waitcnt lgkmcnt(" #n ")" ::: "memory")
; #define PG8_BAR __builtin_amdgcn_s_barrier()
; #define PG8_SCHED __builtin_amdgcn_sched_barrier(0)
; template <class Epi, class Sched, bool ALIGN_EPI = false, bool SP2 = false>
; __device__ __forceinline__ void gemm_phase(PG8_LAS unsigned char* lds, const Gemm g, const Sched& S, const Epi& E) {
;     ...
;             PG8_LDB(B0, 1, 0); PG8_LDB(B1, 1, 1); PG8_SCHED; PG8_LDA(At, 1, 0); PG8_STAGE(PG8_SA(0, 1), a2 + hA, voffA);
;             PG8_WAIT_V(8); PG8_WAIT_L(0); PG8_BAR; PG8_MMA(0, 0, At, B0); PG8_MMA(0, 1, At, B1); PG8_BAR; PG8_SCHED;
;             PG8_LDA(At, 1, 1); PG8_STAGE(PG8_SB(1, 0), b3, voffB); PG8_STAGE(PG8_SB(1, 1), b3 + hB, voffB); PG8_STAGE(PG8_SA(1, 0), a3, voffA);
;             PG8_WAIT_V(8); PG8_WAIT_L(0); PG8_BAR; PG8_MMA(1, 0, At, B0); PG8_MMA(1, 1, At, B1); PG8_BAR; PG8_SCHED;
	s_add_i32 s18, 0, 0x18000
	s_add_i32 s19, 0, 0x1c000
	v_add_u32_e32 v160, s18, v165
	v_add_u32_e32 v164, s19, v165
	ds_read_b128 v[148:151], v160
	ds_read_b128 v[152:155], v160 offset:1024
	ds_read_b128 v[156:159], v160 offset:2048
	ds_read_b128 v[160:163], v160 offset:3072
	ds_read_b128 v[180:183], v164
	ds_read_b128 v[184:187], v164 offset:1024
	ds_read_b128 v[188:191], v164 offset:2048
	ds_read_b128 v[192:195], v164 offset:3072
	s_add_u32 s44, s44, 0x80000
	s_addc_u32 s45, s45, 0
	s_mov_b32 m0, s53
	ds_read_b128 v[196:199], v173 offset:32768
	ds_read_b128 v[200:203], v173 offset:33792
	ds_read_b128 v[204:207], v173 offset:34816
	ds_read_b128 v[208:211], v173 offset:35840
	ds_read_b128 v[212:215], v173 offset:36864
	ds_read_b128 v[216:219], v173 offset:37888
	ds_read_b128 v[224:227], v173 offset:38912
	ds_read_b128 v[228:231], v173 offset:39936
	global_load_lds_dwordx4 v136, s[44:45]
	s_mov_b32 m0, s57
	s_nop 0
	global_load_lds_dwordx4 v132, s[44:45]
	s_waitcnt vmcnt(8)
	s_waitcnt lgkmcnt(0)
	s_barrier
	s_waitcnt lgkmcnt(0)
	v_mfma_f32_16x16x32_bf16 v[126:129], v[148:151], v[196:199], v[126:129]
	v_mfma_f32_16x16x32_bf16 v[122:125], v[156:159], v[196:199], v[122:125]
	v_mfma_f32_16x16x32_bf16 v[110:113], v[148:151], v[204:207], v[110:113]
	v_mfma_f32_16x16x32_bf16 v[106:109], v[156:159], v[204:207], v[106:109]
	v_mfma_f32_16x16x32_bf16 v[94:97], v[148:151], v[212:215], v[94:97]
	v_mfma_f32_16x16x32_bf16 v[90:93], v[156:159], v[212:215], v[90:93]
	v_mfma_f32_16x16x32_bf16 v[78:81], v[148:151], v[224:227], v[78:81]
	v_mfma_f32_16x16x32_bf16 v[74:77], v[156:159], v[224:227], v[74:77]
	v_mfma_f32_16x16x32_bf16 v[126:129], v[152:155], v[200:203], v[126:129]
	v_mfma_f32_16x16x32_bf16 v[122:125], v[160:163], v[200:203], v[122:125]
	v_mfma_f32_16x16x32_bf16 v[110:113], v[152:155], v[208:211], v[110:113]
	v_mfma_f32_16x16x32_bf16 v[106:109], v[160:163], v[208:211], v[106:109]
	v_mfma_f32_16x16x32_bf16 v[94:97], v[152:155], v[216:219], v[94:97]
	v_mfma_f32_16x16x32_bf16 v[90:93], v[160:163], v[216:219], v[90:93]
	v_mfma_f32_16x16x32_bf16 v[78:81], v[152:155], v[228:231], v[78:81]
	v_mfma_f32_16x16x32_bf16 v[74:77], v[160:163], v[228:231], v[74:77]
	v_mfma_f32_16x16x32_bf16 v[118:121], v[180:183], v[196:199], v[118:121]
	v_mfma_f32_16x16x32_bf16 v[114:117], v[188:191], v[196:199], v[114:117]
	v_mfma_f32_16x16x32_bf16 v[102:105], v[180:183], v[204:207], v[102:105]
	v_mfma_f32_16x16x32_bf16 v[98:101], v[188:191], v[204:207], v[98:101]
	s_mov_b32 m0, s60
	v_mfma_f32_16x16x32_bf16 v[86:89], v[180:183], v[212:215], v[86:89]
	global_load_lds_dwordx4 v136, s[78:79]
	v_mfma_f32_16x16x32_bf16 v[82:85], v[188:191], v[212:215], v[82:85]
	s_mov_b32 m0, s61
	v_mfma_f32_16x16x32_bf16 v[70:73], v[180:183], v[224:227], v[70:73]
	global_load_lds_dwordx4 v132, s[78:79]
	v_mfma_f32_16x16x32_bf16 v[66:69], v[188:191], v[224:227], v[66:69]
	v_mfma_f32_16x16x32_bf16 v[118:121], v[184:187], v[200:203], v[118:121]
	v_mfma_f32_16x16x32_bf16 v[114:117], v[192:195], v[200:203], v[114:117]
	v_mfma_f32_16x16x32_bf16 v[102:105], v[184:187], v[208:211], v[102:105]
	v_mfma_f32_16x16x32_bf16 v[98:101], v[192:195], v[208:211], v[98:101]
	v_mfma_f32_16x16x32_bf16 v[86:89], v[184:187], v[216:219], v[86:89]
	v_mfma_f32_16x16x32_bf16 v[82:85], v[192:195], v[216:219], v[82:85]
	v_mfma_f32_16x16x32_bf16 v[70:73], v[184:187], v[228:231], v[70:73]
	v_mfma_f32_16x16x32_bf16 v[66:69], v[192:195], v[228:231], v[66:69]
	s_barrier
	s_add_i32 s18, s18, s49
	s_mov_b32 m0, s18
	ds_read_b128 v[196:199], v173 offset:49152
	ds_read_b128 v[200:203], v173 offset:50176
	ds_read_b128 v[204:207], v173 offset:51200
	ds_read_b128 v[208:211], v173 offset:52224
	ds_read_b128 v[212:215], v173 offset:53248
	ds_read_b128 v[216:219], v173 offset:54272
	ds_read_b128 v[224:227], v173 offset:55296
	ds_read_b128 v[228:231], v173 offset:56320
	global_load_lds_dwordx4 v134, s[76:77]
	s_add_i32 m0, s18, 0x2000
	s_add_u32 s42, s42, 0x80080
	s_addc_u32 s43, s43, 0
	s_add_i32 s18, s19, s49
	global_load_lds_dwordx4 v130, s[76:77]
	s_mov_b32 m0, s18
	s_nop 0
	global_load_lds_dwordx4 v134, s[42:43]
	s_add_i32 m0, s18, 0x2000
	s_nop 0
	global_load_lds_dwordx4 v130, s[42:43]
	s_waitcnt vmcnt(8)
	s_waitcnt lgkmcnt(0)
	s_barrier
	s_waitcnt lgkmcnt(0)
	v_mfma_f32_16x16x32_bf16 v[62:65], v[148:151], v[196:199], v[62:65]
	v_mfma_f32_16x16x32_bf16 v[58:61], v[156:159], v[196:199], v[58:61]
	v_mfma_f32_16x16x32_bf16 v[46:49], v[148:151], v[204:207], v[46:49]
	v_mfma_f32_16x16x32_bf16 v[42:45], v[156:159], v[204:207], v[42:45]
	v_mfma_f32_16x16x32_bf16 v[30:33], v[148:151], v[212:215], v[30:33]
	v_mfma_f32_16x16x32_bf16 v[26:29], v[156:159], v[212:215], v[26:29]
	v_mfma_f32_16x16x32_bf16 v[14:17], v[148:151], v[224:227], v[14:17]
	v_mfma_f32_16x16x32_bf16 v[10:13], v[156:159], v[224:227], v[10:13]
	v_mfma_f32_16x16x32_bf16 v[62:65], v[152:155], v[200:203], v[62:65]
	v_mfma_f32_16x16x32_bf16 v[58:61], v[160:163], v[200:203], v[58:61]
	v_mfma_f32_16x16x32_bf16 v[46:49], v[152:155], v[208:211], v[46:49]
	v_mfma_f32_16x16x32_bf16 v[42:45], v[160:163], v[208:211], v[42:45]
	v_mfma_f32_16x16x32_bf16 v[30:33], v[152:155], v[216:219], v[30:33]
	v_mfma_f32_16x16x32_bf16 v[26:29], v[160:163], v[216:219], v[26:29]
	v_mfma_f32_16x16x32_bf16 v[14:17], v[152:155], v[228:231], v[14:17]
	v_mfma_f32_16x16x32_bf16 v[10:13], v[160:163], v[228:231], v[10:13]
	v_mfma_f32_16x16x32_bf16 v[54:57], v[180:183], v[196:199], v[54:57]
	v_mfma_f32_16x16x32_bf16 v[50:53], v[188:191], v[196:199], v[50:53]
	v_mfma_f32_16x16x32_bf16 v[38:41], v[180:183], v[204:207], v[38:41]
	v_mfma_f32_16x16x32_bf16 v[34:37], v[188:191], v[204:207], v[34:37]
	v_mfma_f32_16x16x32_bf16 v[22:25], v[180:183], v[212:215], v[22:25]
	v_mfma_f32_16x16x32_bf16 v[18:21], v[188:191], v[212:215], v[18:21]
	v_mfma_f32_16x16x32_bf16 v[6:9], v[180:183], v[224:227], v[6:9]
	v_mfma_f32_16x16x32_bf16 v[2:5], v[188:191], v[224:227], v[2:5]
	v_mfma_f32_16x16x32_bf16 v[54:57], v[184:187], v[200:203], v[54:57]
	v_mfma_f32_16x16x32_bf16 v[50:53], v[192:195], v[200:203], v[50:53]
	v_mfma_f32_16x16x32_bf16 v[38:41], v[184:187], v[208:211], v[38:41]
	v_mfma_f32_16x16x32_bf16 v[34:37], v[192:195], v[208:211], v[34:37]
	v_mfma_f32_16x16x32_bf16 v[22:25], v[184:187], v[216:219], v[22:25]
	v_mfma_f32_16x16x32_bf16 v[18:21], v[192:195], v[216:219], v[18:21]
	v_mfma_f32_16x16x32_bf16 v[6:9], v[184:187], v[228:231], v[6:9]
	v_mfma_f32_16x16x32_bf16 v[2:5], v[192:195], v[228:231], v[2:5]
	s_barrier
	s_add_i32 s72, s72, 2
	s_add_u32 s8, s8, 0x100
	s_addc_u32 s9, s9, 0
	s_add_u32 s70, s70, 0x100
	s_addc_u32 s71, s71, 0
	s_cmp_gt_u32 s72, 29
	s_cbranch_scc0 .Lkt_4

; #define PG8_STAGE(bufoff, gbase, voff) do { _Pragma("unroll") for (int _i = 0; _i < 2; ++_i) \
;         __builtin_amdgcn_global_load_lds((const unsigned*)((const char*)(gbase) + (voff)[_i]), (PG8_LAS unsigned*)(lds + (bufoff) + ldsw + _i * 8192), 16, 0, 0); } while (0)
; #define PG8_LDA(dst, b, h) do { _Pragma("unroll") for (int m = 0; m < 4; ++m) _Pragma("unroll") for (int k = 0; k < 2; ++k) dst[m][k] = *(const PG8_LAS bf16x8*)(lds + PG8_SA(b, h) + aoff + m * 2048 + k * 1024); } while (0)
; #define PG8_LDB(dst, b, h) do { _Pragma("unroll") for (int n = 0; n < 2; ++n) _Pragma("unroll") for (int k = 0; k < 2; ++k) dst[n][k] = *(const PG8_LAS bf16x8*)(lds + PG8_SB(b, h) + boff + n * 2048 + k * 1024); } while (0)
; #define PG8_MMA(ai, bj, At, Bt) do { __builtin_amdgcn_s_setprio(1); _Pragma("unroll") for (int m = 0; m < 4; ++m) _Pragma("unroll") for (int n = 0; n < 2; ++n) _Pragma("unroll") for (int k = 0; k < 2; ++k) \
;         acc[ai][bj][m][n] = __builtin_amdgcn_mfma_f32_16x16x32_bf16(Bt[n][k], At[m][k], acc[ai][bj][m][n], 0, 0, 0); __builtin_amdgcn_s_setprio(0); } while (0)
; #define PG8_WAIT_V(n) asm volatile("s_waitcnt vmcnt(" #n ")" ::: "memory")
; #define PG8_WAIT_L(n) asm volatile("s_waitcnt lgkmcnt(" #n ")" ::: "memory")
; #define PG8_BAR __builtin_amdgcn_s_barrier()
; #define PG8_SCHED __builtin_amdgcn_sched_barrier(0)
; template <class Epi, class Sched, bool ALIGN_EPI = false, bool SP2 = false>
; __device__ __forceinline__ void gemm_phase(PG8_LAS unsigned char* lds, const Gemm g, const Sched& S, const Epi& E) {
;     ...
;             PG8_LDB(B0, 0, 0); PG8_LDB(B1, 0, 1); PG8_SCHED; PG8_LDA(At, 0, 0); PG8_STAGE(PG8_SA(1, 1), a1 + hA, voffA);
;             PG8_WAIT_V(8); PG8_WAIT_L(0); PG8_BAR; PG8_MMA(0, 0, At, B0); PG8_MMA(0, 1, At, B1); PG8_BAR; PG8_SCHED;
;             PG8_LDA(At, 0, 1); PG8_STAGE(PG8_SB(0, 0), b2, voffB); PG8_STAGE(PG8_SB(0, 1), b2 + hB, voffB); PG8_STAGE(PG8_SA(0, 0), a2, voffA);
;             PG8_WAIT_V(8); PG8_WAIT_L(0); PG8_BAR; PG8_MMA(1, 0, At, B0); PG8_MMA(1, 1, At, B1); PG8_BAR; PG8_SCHED;
.Lkt_5:
	ds_read_b128 v[130:133], v190
	ds_read_b128 v[134:137], v190 offset:1024
	ds_read_b128 v[138:141], v190 offset:2048
	ds_read_b128 v[142:145], v190 offset:3072
	ds_read_b128 v[146:149], v191
	ds_read_b128 v[150:153], v191 offset:1024
	ds_read_b128 v[170:173], v191 offset:2048
	ds_read_b128 v[174:177], v191 offset:3072
	s_add_u32 s36, s24, 0x100
	s_addc_u32 s37, s25, 0
	s_cmpk_eq_i32 s63, 0x54
	s_cselect_b32 s41, s9, s37
	s_cselect_b32 s40, s8, s36
	s_cselect_b32 s39, s23, s62
	s_cselect_b32 s38, s22, s61
	s_add_i32 m0, s46, 0xc000
	ds_read_b128 v[178:181], v192
	ds_read_b128 v[182:185], v192 offset:1024
	ds_read_b128 v[194:197], v192 offset:2048
	ds_read_b128 v[198:201], v192 offset:3072
	ds_read_b128 v[202:205], v192 offset:4096
	ds_read_b128 v[206:209], v192 offset:5120
	ds_read_b128 v[210:213], v192 offset:6144
	ds_read_b128 v[214:217], v192 offset:7168
	global_load_lds_dwordx4 v162, s[24:25]
	s_add_i32 m0, s46, 0xe000
	s_nop 0
	global_load_lds_dwordx4 v164, s[24:25]
	s_waitcnt vmcnt(8)
	s_waitcnt lgkmcnt(0)
	s_barrier
	s_waitcnt lgkmcnt(0)
	v_mfma_f32_16x16x32_bf16 v[126:129], v[130:133], v[178:181], v[126:129]
	v_mfma_f32_16x16x32_bf16 v[122:125], v[138:141], v[178:181], v[122:125]
	v_mfma_f32_16x16x32_bf16 v[110:113], v[130:133], v[194:197], v[110:113]
	v_mfma_f32_16x16x32_bf16 v[106:109], v[138:141], v[194:197], v[106:109]
	v_mfma_f32_16x16x32_bf16 v[94:97], v[130:133], v[202:205], v[94:97]
	v_mfma_f32_16x16x32_bf16 v[90:93], v[138:141], v[202:205], v[90:93]
	v_mfma_f32_16x16x32_bf16 v[78:81], v[130:133], v[210:213], v[78:81]
	v_mfma_f32_16x16x32_bf16 v[74:77], v[138:141], v[210:213], v[74:77]
	v_mfma_f32_16x16x32_bf16 v[126:129], v[134:137], v[182:185], v[126:129]
	v_mfma_f32_16x16x32_bf16 v[122:125], v[142:145], v[182:185], v[122:125]
	v_mfma_f32_16x16x32_bf16 v[110:113], v[134:137], v[198:201], v[110:113]
	v_mfma_f32_16x16x32_bf16 v[106:109], v[142:145], v[198:201], v[106:109]
	v_mfma_f32_16x16x32_bf16 v[94:97], v[134:137], v[206:209], v[94:97]
	v_mfma_f32_16x16x32_bf16 v[90:93], v[142:145], v[206:209], v[90:93]
	v_mfma_f32_16x16x32_bf16 v[78:81], v[134:137], v[214:217], v[78:81]
	v_mfma_f32_16x16x32_bf16 v[74:77], v[142:145], v[214:217], v[74:77]
	v_mfma_f32_16x16x32_bf16 v[118:121], v[146:149], v[178:181], v[118:121]
	v_mfma_f32_16x16x32_bf16 v[114:117], v[170:173], v[178:181], v[114:117]
	v_mfma_f32_16x16x32_bf16 v[102:105], v[146:149], v[194:197], v[102:105]
	v_mfma_f32_16x16x32_bf16 v[98:101], v[170:173], v[194:197], v[98:101]
	s_mov_b32 m0, s46
	v_mfma_f32_16x16x32_bf16 v[86:89], v[146:149], v[202:205], v[86:89]
	global_load_lds_dwordx4 v154, s[40:41]
	v_mfma_f32_16x16x32_bf16 v[82:85], v[170:173], v[202:205], v[82:85]
	s_mov_b32 m0, s47
	v_mfma_f32_16x16x32_bf16 v[70:73], v[146:149], v[210:213], v[70:73]
	global_load_lds_dwordx4 v158, s[40:41]
	v_mfma_f32_16x16x32_bf16 v[66:69], v[170:173], v[210:213], v[66:69]
	v_mfma_f32_16x16x32_bf16 v[118:121], v[150:153], v[182:185], v[118:121]
	v_mfma_f32_16x16x32_bf16 v[114:117], v[174:177], v[182:185], v[114:117]
	v_mfma_f32_16x16x32_bf16 v[102:105], v[150:153], v[198:201], v[102:105]
	v_mfma_f32_16x16x32_bf16 v[98:101], v[174:177], v[198:201], v[98:101]
	v_mfma_f32_16x16x32_bf16 v[86:89], v[150:153], v[206:209], v[86:89]
	v_mfma_f32_16x16x32_bf16 v[82:85], v[174:177], v[206:209], v[82:85]
	v_mfma_f32_16x16x32_bf16 v[70:73], v[150:153], v[214:217], v[70:73]
	v_mfma_f32_16x16x32_bf16 v[66:69], v[174:177], v[214:217], v[66:69]
	s_barrier
	s_add_i32 s18, s55, s45
	s_add_u32 s76, s38, s16
	s_addc_u32 s77, s39, s17
	s_mov_b32 m0, s18
	ds_read_b128 v[178:181], v192 offset:16384
	ds_read_b128 v[182:185], v192 offset:17408
	ds_read_b128 v[194:197], v192 offset:18432
	ds_read_b128 v[198:201], v192 offset:19456
	ds_read_b128 v[202:205], v192 offset:20480
	ds_read_b128 v[206:209], v192 offset:21504
	ds_read_b128 v[210:213], v192 offset:22528
	ds_read_b128 v[214:217], v192 offset:23552
	global_load_lds_dwordx4 v156, s[38:39]
	s_add_i32 m0, s18, 0x2000
	s_add_u32 s24, s38, 0x160000
	s_addc_u32 s25, s39, 0
	s_add_i32 s18, s56, s45
	global_load_lds_dwordx4 v160, s[38:39]
	s_mov_b32 m0, s18
	s_nop 0
	global_load_lds_dwordx4 v156, s[24:25]
	s_add_i32 m0, s18, 0x2000
	s_nop 0
	global_load_lds_dwordx4 v160, s[24:25]
	s_add_u32 s78, s40, s16
	s_addc_u32 s79, s41, s17
	s_waitcnt vmcnt(8)
	s_waitcnt lgkmcnt(0)
	s_barrier
	s_waitcnt lgkmcnt(0)
	v_mfma_f32_16x16x32_bf16 v[62:65], v[130:133], v[178:181], v[62:65]
	v_mfma_f32_16x16x32_bf16 v[58:61], v[138:141], v[178:181], v[58:61]
	v_mfma_f32_16x16x32_bf16 v[46:49], v[130:133], v[194:197], v[46:49]
	v_mfma_f32_16x16x32_bf16 v[42:45], v[138:141], v[194:197], v[42:45]
	v_mfma_f32_16x16x32_bf16 v[30:33], v[130:133], v[202:205], v[30:33]
	v_mfma_f32_16x16x32_bf16 v[26:29], v[138:141], v[202:205], v[26:29]
	v_mfma_f32_16x16x32_bf16 v[14:17], v[130:133], v[210:213], v[14:17]
	v_mfma_f32_16x16x32_bf16 v[10:13], v[138:141], v[210:213], v[10:13]
	v_mfma_f32_16x16x32_bf16 v[62:65], v[134:137], v[182:185], v[62:65]
	v_mfma_f32_16x16x32_bf16 v[58:61], v[142:145], v[182:185], v[58:61]
	v_mfma_f32_16x16x32_bf16 v[46:49], v[134:137], v[198:201], v[46:49]
	v_mfma_f32_16x16x32_bf16 v[42:45], v[142:145], v[198:201], v[42:45]
	v_mfma_f32_16x16x32_bf16 v[30:33], v[134:137], v[206:209], v[30:33]
	v_mfma_f32_16x16x32_bf16 v[26:29], v[142:145], v[206:209], v[26:29]
	v_mfma_f32_16x16x32_bf16 v[14:17], v[134:137], v[214:217], v[14:17]
	v_mfma_f32_16x16x32_bf16 v[10:13], v[142:145], v[214:217], v[10:13]
	v_mfma_f32_16x16x32_bf16 v[54:57], v[146:149], v[178:181], v[54:57]
	v_mfma_f32_16x16x32_bf16 v[50:53], v[170:173], v[178:181], v[50:53]
	v_mfma_f32_16x16x32_bf16 v[38:41], v[146:149], v[194:197], v[38:41]
	v_mfma_f32_16x16x32_bf16 v[34:37], v[170:173], v[194:197], v[34:37]
	v_mfma_f32_16x16x32_bf16 v[22:25], v[146:149], v[202:205], v[22:25]
	v_mfma_f32_16x16x32_bf16 v[18:21], v[170:173], v[202:205], v[18:21]
	v_mfma_f32_16x16x32_bf16 v[6:9], v[146:149], v[210:213], v[6:9]
	v_mfma_f32_16x16x32_bf16 v[2:5], v[170:173], v[210:213], v[2:5]
	v_mfma_f32_16x16x32_bf16 v[54:57], v[150:153], v[182:185], v[54:57]
	v_mfma_f32_16x16x32_bf16 v[50:53], v[174:177], v[182:185], v[50:53]
	v_mfma_f32_16x16x32_bf16 v[38:41], v[150:153], v[198:201], v[38:41]
	v_mfma_f32_16x16x32_bf16 v[34:37], v[174:177], v[198:201], v[34:37]
	v_mfma_f32_16x16x32_bf16 v[22:25], v[150:153], v[206:209], v[22:25]
	v_mfma_f32_16x16x32_bf16 v[18:21], v[174:177], v[206:209], v[18:21]
	v_mfma_f32_16x16x32_bf16 v[6:9], v[150:153], v[214:217], v[6:9]
	v_mfma_f32_16x16x32_bf16 v[2:5], v[174:177], v[214:217], v[2:5]
	s_barrier
; #define PG8_STAGE(bufoff, gbase, voff) do { _Pragma("unroll") for (int _i = 0; _i < 2; ++_i) \
;         __builtin_amdgcn_global_load_lds((const unsigned*)((const char*)(gbase) + (voff)[_i]), (PG8_LAS unsigned*)(lds + (bufoff) + ldsw + _i * 8192), 16, 0, 0); } while (0)
; #define PG8_LDA(dst, b, h) do { _Pragma("unroll") for (int m = 0; m < 4; ++m) _Pragma("unroll") for (int k = 0; k < 2; ++k) dst[m][k] = *(const PG8_LAS bf16x8*)(lds + PG8_SA(b, h) + aoff + m * 2048 + k * 1024); } while (0)
; #define PG8_LDB(dst, b, h) do { _Pragma("unroll") for (int n = 0; n < 2; ++n) _Pragma("unroll") for (int k = 0; k < 2; ++k) dst[n][k] = *(const PG8_LAS bf16x8*)(lds + PG8_SB(b, h) + boff + n * 2048 + k * 1024); } while (0)
; #define PG8_MMA(ai, bj, At, Bt) do { __builtin_amdgcn_s_setprio(1); _Pragma("unroll") for (int m = 0; m < 4; ++m) _Pragma("unroll") for (int n = 0; n < 2; ++n) _Pragma("unroll") for (int k = 0; k < 2; ++k) \
;         acc[ai][bj][m][n] = __builtin_amdgcn_mfma_f32_16x16x32_bf16(Bt[n][k], At[m][k], acc[ai][bj][m][n], 0, 0, 0); __builtin_amdgcn_s_setprio(0); } while (0)
; #define PG8_WAIT_V(n) asm volatile("s_waitcnt vmcnt(" #n ")" ::: "memory")
; #define PG8_WAIT_L(n) asm volatile("s_waitcnt lgkmcnt(" #n ")" ::: "memory")
; #define PG8_BAR __builtin_amdgcn_s_barrier()
; #define PG8_SCHED __builtin_amdgcn_sched_barrier(0)
; template <class Epi, class Sched, bool ALIGN_EPI = false, bool SP2 = false>
; __device__ __forceinline__ void gemm_phase(PG8_LAS unsigned char* lds, const Gemm g, const Sched& S, const Epi& E) {
;     ...
;             PG8_LDB(B0, 1, 0); PG8_LDB(B1, 1, 1); PG8_SCHED; PG8_LDA(At, 1, 0); PG8_STAGE(PG8_SA(0, 1), a2 + hA, voffA);
;             PG8_WAIT_V(8); PG8_WAIT_L(0); PG8_BAR; PG8_MMA(0, 0, At, B0); PG8_MMA(0, 1, At, B1); PG8_BAR; PG8_SCHED;
;             PG8_LDA(At, 1, 1); PG8_STAGE(PG8_SB(1, 0), b3, voffB); PG8_STAGE(PG8_SB(1, 1), b3 + hB, voffB); PG8_STAGE(PG8_SA(1, 0), a3, voffA);
;             PG8_WAIT_V(8); PG8_WAIT_L(0); PG8_BAR; PG8_MMA(1, 0, At, B0); PG8_MMA(1, 1, At, B1); PG8_BAR; PG8_SCHED;
	s_add_i32 s18, 0, 0x18000
	s_add_i32 s19, 0, 0x1c000
	v_add_u32_e32 v142, s18, v188
	v_add_u32_e32 v174, s19, v188
	ds_read_b128 v[130:133], v142
	ds_read_b128 v[134:137], v142 offset:1024
	ds_read_b128 v[138:141], v142 offset:2048
	ds_read_b128 v[142:145], v142 offset:3072
	ds_read_b128 v[146:149], v174
	ds_read_b128 v[150:153], v174 offset:1024
	ds_read_b128 v[170:173], v174 offset:2048
	ds_read_b128 v[174:177], v174 offset:3072
	s_add_u32 s24, s40, 0x160000
	s_addc_u32 s25, s41, 0
	s_mov_b32 m0, s48
	ds_read_b128 v[178:181], v192 offset:32768
	ds_read_b128 v[182:185], v192 offset:33792
	ds_read_b128 v[194:197], v192 offset:34816
	ds_read_b128 v[198:201], v192 offset:35840
	ds_read_b128 v[202:205], v192 offset:36864
	ds_read_b128 v[206:209], v192 offset:37888
	ds_read_b128 v[210:213], v192 offset:38912
	ds_read_b128 v[214:217], v192 offset:39936
	global_load_lds_dwordx4 v154, s[24:25]
	s_mov_b32 m0, s49
	s_nop 0
	global_load_lds_dwordx4 v158, s[24:25]
	s_waitcnt vmcnt(8)
	s_waitcnt lgkmcnt(0)
	s_barrier
	s_waitcnt lgkmcnt(0)
	v_mfma_f32_16x16x32_bf16 v[126:129], v[130:133], v[178:181], v[126:129]
	v_mfma_f32_16x16x32_bf16 v[122:125], v[138:141], v[178:181], v[122:125]
	v_mfma_f32_16x16x32_bf16 v[110:113], v[130:133], v[194:197], v[110:113]
	v_mfma_f32_16x16x32_bf16 v[106:109], v[138:141], v[194:197], v[106:109]
	v_mfma_f32_16x16x32_bf16 v[94:97], v[130:133], v[202:205], v[94:97]
	v_mfma_f32_16x16x32_bf16 v[90:93], v[138:141], v[202:205], v[90:93]
	v_mfma_f32_16x16x32_bf16 v[78:81], v[130:133], v[210:213], v[78:81]
	v_mfma_f32_16x16x32_bf16 v[74:77], v[138:141], v[210:213], v[74:77]
	v_mfma_f32_16x16x32_bf16 v[126:129], v[134:137], v[182:185], v[126:129]
	v_mfma_f32_16x16x32_bf16 v[122:125], v[142:145], v[182:185], v[122:125]
	v_mfma_f32_16x16x32_bf16 v[110:113], v[134:137], v[198:201], v[110:113]
	v_mfma_f32_16x16x32_bf16 v[106:109], v[142:145], v[198:201], v[106:109]
	v_mfma_f32_16x16x32_bf16 v[94:97], v[134:137], v[206:209], v[94:97]
	v_mfma_f32_16x16x32_bf16 v[90:93], v[142:145], v[206:209], v[90:93]
	v_mfma_f32_16x16x32_bf16 v[78:81], v[134:137], v[214:217], v[78:81]
	v_mfma_f32_16x16x32_bf16 v[74:77], v[142:145], v[214:217], v[74:77]
	v_mfma_f32_16x16x32_bf16 v[118:121], v[146:149], v[178:181], v[118:121]
	v_mfma_f32_16x16x32_bf16 v[114:117], v[170:173], v[178:181], v[114:117]
	v_mfma_f32_16x16x32_bf16 v[102:105], v[146:149], v[194:197], v[102:105]
	v_mfma_f32_16x16x32_bf16 v[98:101], v[170:173], v[194:197], v[98:101]
	s_mov_b32 m0, s52
	v_mfma_f32_16x16x32_bf16 v[86:89], v[146:149], v[202:205], v[86:89]
	global_load_lds_dwordx4 v154, s[78:79]
	v_mfma_f32_16x16x32_bf16 v[82:85], v[170:173], v[202:205], v[82:85]
	s_mov_b32 m0, s53
	v_mfma_f32_16x16x32_bf16 v[70:73], v[146:149], v[210:213], v[70:73]
	global_load_lds_dwordx4 v158, s[78:79]
	v_mfma_f32_16x16x32_bf16 v[66:69], v[170:173], v[210:213], v[66:69]
	v_mfma_f32_16x16x32_bf16 v[118:121], v[150:153], v[182:185], v[118:121]
	v_mfma_f32_16x16x32_bf16 v[114:117], v[174:177], v[182:185], v[114:117]
	v_mfma_f32_16x16x32_bf16 v[102:105], v[150:153], v[198:201], v[102:105]
	v_mfma_f32_16x16x32_bf16 v[98:101], v[174:177], v[198:201], v[98:101]
	v_mfma_f32_16x16x32_bf16 v[86:89], v[150:153], v[206:209], v[86:89]
	v_mfma_f32_16x16x32_bf16 v[82:85], v[174:177], v[206:209], v[82:85]
	v_mfma_f32_16x16x32_bf16 v[70:73], v[150:153], v[214:217], v[70:73]
	v_mfma_f32_16x16x32_bf16 v[66:69], v[174:177], v[214:217], v[66:69]
	s_barrier
	s_add_i32 s18, s18, s45
	s_mov_b32 m0, s18
	ds_read_b128 v[178:181], v192 offset:49152
	ds_read_b128 v[182:185], v192 offset:50176
	ds_read_b128 v[194:197], v192 offset:51200
	ds_read_b128 v[198:201], v192 offset:52224
	ds_read_b128 v[202:205], v192 offset:53248
	ds_read_b128 v[206:209], v192 offset:54272
	ds_read_b128 v[210:213], v192 offset:55296
	ds_read_b128 v[214:217], v192 offset:56320
	global_load_lds_dwordx4 v156, s[76:77]
	s_add_i32 m0, s18, 0x2000
	s_add_u32 s24, s38, 0x160080
	s_addc_u32 s25, s39, 0
	s_add_i32 s18, s19, s45
	global_load_lds_dwordx4 v160, s[76:77]
	s_mov_b32 m0, s18
	s_nop 0
	global_load_lds_dwordx4 v156, s[24:25]
	s_add_i32 m0, s18, 0x2000
	s_nop 0
	global_load_lds_dwordx4 v160, s[24:25]
	s_waitcnt vmcnt(8)
	s_waitcnt lgkmcnt(0)
	s_barrier
	s_waitcnt lgkmcnt(0)
	v_mfma_f32_16x16x32_bf16 v[62:65], v[130:133], v[178:181], v[62:65]
	v_mfma_f32_16x16x32_bf16 v[58:61], v[138:141], v[178:181], v[58:61]
	v_mfma_f32_16x16x32_bf16 v[46:49], v[130:133], v[194:197], v[46:49]
	v_mfma_f32_16x16x32_bf16 v[42:45], v[138:141], v[194:197], v[42:45]
	v_mfma_f32_16x16x32_bf16 v[30:33], v[130:133], v[202:205], v[30:33]
	v_mfma_f32_16x16x32_bf16 v[26:29], v[138:141], v[202:205], v[26:29]
	v_mfma_f32_16x16x32_bf16 v[14:17], v[130:133], v[210:213], v[14:17]
	v_mfma_f32_16x16x32_bf16 v[10:13], v[138:141], v[210:213], v[10:13]
	v_mfma_f32_16x16x32_bf16 v[62:65], v[134:137], v[182:185], v[62:65]
	v_mfma_f32_16x16x32_bf16 v[58:61], v[142:145], v[182:185], v[58:61]
	v_mfma_f32_16x16x32_bf16 v[46:49], v[134:137], v[198:201], v[46:49]
	v_mfma_f32_16x16x32_bf16 v[42:45], v[142:145], v[198:201], v[42:45]
	v_mfma_f32_16x16x32_bf16 v[30:33], v[134:137], v[206:209], v[30:33]
	v_mfma_f32_16x16x32_bf16 v[26:29], v[142:145], v[206:209], v[26:29]
	v_mfma_f32_16x16x32_bf16 v[14:17], v[134:137], v[214:217], v[14:17]
	v_mfma_f32_16x16x32_bf16 v[10:13], v[142:145], v[214:217], v[10:13]
	v_mfma_f32_16x16x32_bf16 v[54:57], v[146:149], v[178:181], v[54:57]
	v_mfma_f32_16x16x32_bf16 v[50:53], v[170:173], v[178:181], v[50:53]
	v_mfma_f32_16x16x32_bf16 v[38:41], v[146:149], v[194:197], v[38:41]
	v_mfma_f32_16x16x32_bf16 v[34:37], v[170:173], v[194:197], v[34:37]
	v_mfma_f32_16x16x32_bf16 v[22:25], v[146:149], v[202:205], v[22:25]
	v_mfma_f32_16x16x32_bf16 v[18:21], v[170:173], v[202:205], v[18:21]
	v_mfma_f32_16x16x32_bf16 v[6:9], v[146:149], v[210:213], v[6:9]
	v_mfma_f32_16x16x32_bf16 v[2:5], v[170:173], v[210:213], v[2:5]
	v_mfma_f32_16x16x32_bf16 v[54:57], v[150:153], v[182:185], v[54:57]
	v_mfma_f32_16x16x32_bf16 v[50:53], v[174:177], v[182:185], v[50:53]
	v_mfma_f32_16x16x32_bf16 v[38:41], v[150:153], v[198:201], v[38:41]
	v_mfma_f32_16x16x32_bf16 v[34:37], v[174:177], v[198:201], v[34:37]
	v_mfma_f32_16x16x32_bf16 v[22:25], v[150:153], v[206:209], v[22:25]
	v_mfma_f32_16x16x32_bf16 v[18:21], v[174:177], v[206:209], v[18:21]
	v_mfma_f32_16x16x32_bf16 v[6:9], v[150:153], v[214:217], v[6:9]
	v_mfma_f32_16x16x32_bf16 v[2:5], v[174:177], v[214:217], v[2:5]
	s_barrier
	s_add_i32 s63, s63, 2
	s_add_u32 s61, s61, 0x100
	s_addc_u32 s62, s62, 0
	s_cmpk_gt_u32 s63, 0x55
	s_mov_b64 s[24:25], s[36:37]
	s_cbranch_scc0 .Lkt_5
